# GEMM K-loops: all per-segment s_setprio toggles removed
# speedup vs baseline: 1.0057x; 1.0057x over previous
.LBB0_159:
	s_ashr_i32 s29, s28, 31
	s_lshl_b64 s[24:25], s[28:29], 19
	s_add_u32 s24, s34, s24
	s_addc_u32 s25, s35, s25
	s_and_b64 s[30:31], s[18:19], exec
	s_cselect_b32 s29, s25, s41
	s_cselect_b32 s43, s24, s40
	s_ashr_i32 s21, s20, 31
	s_lshl_b64 s[30:31], s[20:21], 19
	s_add_u32 s30, s36, s30
	s_addc_u32 s31, s37, s31
	s_and_b64 s[56:57], s[18:19], exec
	s_cselect_b32 s21, s31, s27
	s_cselect_b32 s55, s30, s26
	s_add_u32 s40, s40, 0x40080
	s_addc_u32 s41, s41, 0
	s_add_u32 s56, s26, 0x100
	s_addc_u32 s57, s27, 0
	s_mov_b32 s58, -2
	s_add_u32 s26, s40, 0xfffc0080
	s_addc_u32 s27, s41, -1
	s_add_i32 s59, 0, 0x10000
	s_cmp_eq_u32 s58, 12
	s_cselect_b32 vcc_hi, s29, s27
	s_cselect_b32 vcc_lo, s43, s26
	v_add_u32_e32 v0, s59, v167
	s_cselect_b32 s27, s21, s57
	s_cselect_b32 s26, s55, s56
	s_add_i32 s62, 0, 0x14000
	ds_read_b128 v[142:145], v0
	ds_read_b128 v[146:149], v0 offset:1024
	ds_read_b128 v[150:153], v0 offset:2048
	ds_read_b128 v[154:157], v0 offset:3072
	v_add_u32_e32 v0, s62, v167
	ds_read_b128 v[158:161], v0
	ds_read_b128 v[162:165], v0 offset:1024
	ds_read_b128 v[174:177], v0 offset:2048
	ds_read_b128 v[178:181], v0 offset:3072
	v_lshl_add_u64 v[214:215], s[40:41], 0, v[138:139]
	s_add_i32 m0, s23, 0xc000
	ds_read_b128 v[182:185], v173
	ds_read_b128 v[186:189], v173 offset:1024
	ds_read_b128 v[190:193], v173 offset:2048
	ds_read_b128 v[194:197], v173 offset:3072
	ds_read_b128 v[198:201], v173 offset:4096
	ds_read_b128 v[202:205], v173 offset:5120
	ds_read_b128 v[206:209], v173 offset:6144
	ds_read_b128 v[210:213], v173 offset:7168
	global_load_lds_dwordx4 v[214:215], off
	v_lshl_add_u64 v[214:215], s[40:41], 0, v[140:141]
	s_add_i32 m0, s23, 0xe000
	s_nop 0
	global_load_lds_dwordx4 v[214:215], off
	s_waitcnt vmcnt(8)
	s_waitcnt lgkmcnt(0)
	s_barrier
	s_waitcnt lgkmcnt(0)
	v_mfma_f32_16x16x32_bf16 v[126:129], v[142:145], v[182:185], 0
	v_mfma_f32_16x16x32_bf16 v[122:125], v[150:153], v[182:185], 0
	v_mfma_f32_16x16x32_bf16 v[118:121], v[142:145], v[190:193], 0
	v_mfma_f32_16x16x32_bf16 v[114:117], v[150:153], v[190:193], 0
	v_mfma_f32_16x16x32_bf16 v[110:113], v[142:145], v[198:201], 0
	v_mfma_f32_16x16x32_bf16 v[106:109], v[150:153], v[198:201], 0
	v_mfma_f32_16x16x32_bf16 v[102:105], v[142:145], v[206:209], 0
	v_mfma_f32_16x16x32_bf16 v[98:101], v[150:153], v[206:209], 0
	v_mfma_f32_16x16x32_bf16 v[126:129], v[146:149], v[186:189], v[126:129]
	v_mfma_f32_16x16x32_bf16 v[122:125], v[154:157], v[186:189], v[122:125]
	v_mfma_f32_16x16x32_bf16 v[118:121], v[146:149], v[194:197], v[118:121]
	v_mfma_f32_16x16x32_bf16 v[114:117], v[154:157], v[194:197], v[114:117]
	v_mfma_f32_16x16x32_bf16 v[110:113], v[146:149], v[202:205], v[110:113]
	v_mfma_f32_16x16x32_bf16 v[106:109], v[154:157], v[202:205], v[106:109]
	v_mfma_f32_16x16x32_bf16 v[102:105], v[146:149], v[210:213], v[102:105]
	v_mfma_f32_16x16x32_bf16 v[98:101], v[154:157], v[210:213], v[98:101]
	v_mfma_f32_16x16x32_bf16 v[82:85], v[158:161], v[182:185], 0
	v_mfma_f32_16x16x32_bf16 v[74:77], v[174:177], v[182:185], 0
	v_mfma_f32_16x16x32_bf16 v[70:73], v[158:161], v[190:193], 0
	v_mfma_f32_16x16x32_bf16 v[62:65], v[174:177], v[190:193], 0
	v_mfma_f32_16x16x32_bf16 v[54:57], v[158:161], v[198:201], 0
	v_mfma_f32_16x16x32_bf16 v[46:49], v[174:177], v[198:201], 0
	v_mfma_f32_16x16x32_bf16 v[38:41], v[158:161], v[206:209], 0
	v_mfma_f32_16x16x32_bf16 v[34:37], v[174:177], v[206:209], 0
	v_mfma_f32_16x16x32_bf16 v[82:85], v[162:165], v[186:189], v[82:85]
	v_mfma_f32_16x16x32_bf16 v[74:77], v[178:181], v[186:189], v[74:77]
	v_mfma_f32_16x16x32_bf16 v[70:73], v[162:165], v[194:197], v[70:73]
	v_mfma_f32_16x16x32_bf16 v[62:65], v[178:181], v[194:197], v[62:65]
	v_mfma_f32_16x16x32_bf16 v[54:57], v[162:165], v[202:205], v[54:57]
	v_mfma_f32_16x16x32_bf16 v[46:49], v[178:181], v[202:205], v[46:49]
	v_mfma_f32_16x16x32_bf16 v[38:41], v[162:165], v[210:213], v[38:41]
	v_mfma_f32_16x16x32_bf16 v[34:37], v[178:181], v[210:213], v[34:37]
	s_barrier
	s_add_i32 s59, s59, s44
	v_lshl_add_u64 v[214:215], s[26:27], 0, v[132:133]
	s_mov_b32 m0, s59
	ds_read_b128 v[182:185], v173 offset:16384
	ds_read_b128 v[186:189], v173 offset:17408
	ds_read_b128 v[190:193], v173 offset:18432
	ds_read_b128 v[194:197], v173 offset:19456
	ds_read_b128 v[198:201], v173 offset:20480
	ds_read_b128 v[202:205], v173 offset:21504
	ds_read_b128 v[206:209], v173 offset:22528
	ds_read_b128 v[210:213], v173 offset:23552
	global_load_lds_dwordx4 v[214:215], off
	s_add_i32 m0, s59, 0x2000
	s_add_u32 s60, s26, 0x40000
	v_lshl_add_u64 v[216:217], s[26:27], 0, v[136:137]
	s_addc_u32 s61, s27, 0
	s_add_i32 s59, s62, s44
	global_load_lds_dwordx4 v[216:217], off
	v_lshl_add_u64 v[218:219], s[60:61], 0, v[132:133]
	s_mov_b32 m0, s59
	v_lshl_add_u64 v[220:221], vcc, 0, v[134:135]
	global_load_lds_dwordx4 v[218:219], off
	v_lshl_add_u64 v[218:219], s[60:61], 0, v[136:137]
	s_add_i32 m0, s59, 0x2000
	s_nop 0
	global_load_lds_dwordx4 v[218:219], off
	v_lshl_add_u64 v[218:219], vcc, 0, v[130:131]
	s_mov_b32 m0, s23
	s_nop 0
	global_load_lds_dwordx4 v[218:219], off
	s_mov_b32 m0, s45
	s_nop 0
	global_load_lds_dwordx4 v[220:221], off
	s_waitcnt vmcnt(8)
	s_waitcnt lgkmcnt(0)
	s_barrier
	s_waitcnt lgkmcnt(0)
	v_mfma_f32_16x16x32_bf16 v[94:97], v[142:145], v[182:185], 0
	v_mfma_f32_16x16x32_bf16 v[90:93], v[150:153], v[182:185], 0
	v_mfma_f32_16x16x32_bf16 v[86:89], v[142:145], v[190:193], 0
	v_mfma_f32_16x16x32_bf16 v[78:81], v[150:153], v[190:193], 0
	v_mfma_f32_16x16x32_bf16 v[66:69], v[142:145], v[198:201], 0
	v_mfma_f32_16x16x32_bf16 v[58:61], v[150:153], v[198:201], 0
	v_mfma_f32_16x16x32_bf16 v[50:53], v[142:145], v[206:209], 0
	v_mfma_f32_16x16x32_bf16 v[42:45], v[150:153], v[206:209], 0
	v_mfma_f32_16x16x32_bf16 v[94:97], v[146:149], v[186:189], v[94:97]
	v_mfma_f32_16x16x32_bf16 v[90:93], v[154:157], v[186:189], v[90:93]
	v_mfma_f32_16x16x32_bf16 v[86:89], v[146:149], v[194:197], v[86:89]
	v_mfma_f32_16x16x32_bf16 v[78:81], v[154:157], v[194:197], v[78:81]
	v_mfma_f32_16x16x32_bf16 v[66:69], v[146:149], v[202:205], v[66:69]
	v_mfma_f32_16x16x32_bf16 v[58:61], v[154:157], v[202:205], v[58:61]
	v_mfma_f32_16x16x32_bf16 v[50:53], v[146:149], v[210:213], v[50:53]
	v_mfma_f32_16x16x32_bf16 v[42:45], v[154:157], v[210:213], v[42:45]
	v_mfma_f32_16x16x32_bf16 v[30:33], v[158:161], v[182:185], 0
	v_mfma_f32_16x16x32_bf16 v[26:29], v[174:177], v[182:185], 0
	v_mfma_f32_16x16x32_bf16 v[22:25], v[158:161], v[190:193], 0
	v_mfma_f32_16x16x32_bf16 v[18:21], v[174:177], v[190:193], 0
	v_mfma_f32_16x16x32_bf16 v[14:17], v[158:161], v[198:201], 0
	v_mfma_f32_16x16x32_bf16 v[10:13], v[174:177], v[198:201], 0
	v_mfma_f32_16x16x32_bf16 v[6:9], v[158:161], v[206:209], 0
	v_mfma_f32_16x16x32_bf16 v[2:5], v[174:177], v[206:209], 0
	v_mfma_f32_16x16x32_bf16 v[30:33], v[162:165], v[186:189], v[30:33]
	v_mfma_f32_16x16x32_bf16 v[26:29], v[178:181], v[186:189], v[26:29]
	v_mfma_f32_16x16x32_bf16 v[22:25], v[162:165], v[194:197], v[22:25]
	v_mfma_f32_16x16x32_bf16 v[18:21], v[178:181], v[194:197], v[18:21]
	v_mfma_f32_16x16x32_bf16 v[14:17], v[162:165], v[202:205], v[14:17]
	v_mfma_f32_16x16x32_bf16 v[10:13], v[178:181], v[202:205], v[10:13]
	v_mfma_f32_16x16x32_bf16 v[6:9], v[162:165], v[210:213], v[6:9]
	v_mfma_f32_16x16x32_bf16 v[2:5], v[178:181], v[210:213], v[2:5]
	s_barrier
	s_add_i32 s59, 0, 0x18000
	v_add_u32_e32 v0, s59, v167
	s_add_i32 s62, 0, 0x1c000
	ds_read_b128 v[142:145], v0
	ds_read_b128 v[146:149], v0 offset:1024
	ds_read_b128 v[150:153], v0 offset:2048
	ds_read_b128 v[154:157], v0 offset:3072
	v_add_u32_e32 v0, s62, v167
	ds_read_b128 v[158:161], v0
	ds_read_b128 v[162:165], v0 offset:1024
	ds_read_b128 v[174:177], v0 offset:2048
	ds_read_b128 v[178:181], v0 offset:3072
	s_add_u32 s60, vcc_lo, 0x40000
	s_addc_u32 s61, vcc_hi, 0
	s_mov_b32 m0, s47
	v_lshl_add_u64 v[222:223], s[60:61], 0, v[130:131]
	ds_read_b128 v[182:185], v173 offset:32768
	ds_read_b128 v[186:189], v173 offset:33792
	ds_read_b128 v[190:193], v173 offset:34816
	ds_read_b128 v[194:197], v173 offset:35840
	ds_read_b128 v[198:201], v173 offset:36864
	ds_read_b128 v[202:205], v173 offset:37888
	ds_read_b128 v[206:209], v173 offset:38912
	ds_read_b128 v[210:213], v173 offset:39936
	global_load_lds_dwordx4 v[222:223], off
	v_lshl_add_u64 v[222:223], s[60:61], 0, v[134:135]
	s_mov_b32 m0, s49
	s_nop 0
	global_load_lds_dwordx4 v[222:223], off
	s_waitcnt vmcnt(8)
	s_waitcnt lgkmcnt(0)
	s_barrier
	s_waitcnt lgkmcnt(0)
	v_mfma_f32_16x16x32_bf16 v[126:129], v[142:145], v[182:185], v[126:129]
	v_mfma_f32_16x16x32_bf16 v[122:125], v[150:153], v[182:185], v[122:125]
	v_mfma_f32_16x16x32_bf16 v[118:121], v[142:145], v[190:193], v[118:121]
	v_mfma_f32_16x16x32_bf16 v[114:117], v[150:153], v[190:193], v[114:117]
	v_mfma_f32_16x16x32_bf16 v[110:113], v[142:145], v[198:201], v[110:113]
	v_mfma_f32_16x16x32_bf16 v[106:109], v[150:153], v[198:201], v[106:109]
	v_mfma_f32_16x16x32_bf16 v[102:105], v[142:145], v[206:209], v[102:105]
	v_mfma_f32_16x16x32_bf16 v[98:101], v[150:153], v[206:209], v[98:101]
	v_mfma_f32_16x16x32_bf16 v[126:129], v[146:149], v[186:189], v[126:129]
	v_mfma_f32_16x16x32_bf16 v[122:125], v[154:157], v[186:189], v[122:125]
	v_mfma_f32_16x16x32_bf16 v[118:121], v[146:149], v[194:197], v[118:121]
	v_mfma_f32_16x16x32_bf16 v[114:117], v[154:157], v[194:197], v[114:117]
	v_mfma_f32_16x16x32_bf16 v[110:113], v[146:149], v[202:205], v[110:113]
	v_mfma_f32_16x16x32_bf16 v[106:109], v[154:157], v[202:205], v[106:109]
	v_mfma_f32_16x16x32_bf16 v[102:105], v[146:149], v[210:213], v[102:105]
	v_mfma_f32_16x16x32_bf16 v[98:101], v[154:157], v[210:213], v[98:101]
	v_mfma_f32_16x16x32_bf16 v[82:85], v[158:161], v[182:185], v[82:85]
	v_mfma_f32_16x16x32_bf16 v[74:77], v[174:177], v[182:185], v[74:77]
	v_mfma_f32_16x16x32_bf16 v[70:73], v[158:161], v[190:193], v[70:73]
	v_mfma_f32_16x16x32_bf16 v[62:65], v[174:177], v[190:193], v[62:65]
	v_mfma_f32_16x16x32_bf16 v[54:57], v[158:161], v[198:201], v[54:57]
	v_mfma_f32_16x16x32_bf16 v[46:49], v[174:177], v[198:201], v[46:49]
	v_mfma_f32_16x16x32_bf16 v[38:41], v[158:161], v[206:209], v[38:41]
	v_mfma_f32_16x16x32_bf16 v[34:37], v[174:177], v[206:209], v[34:37]
	v_mfma_f32_16x16x32_bf16 v[82:85], v[162:165], v[186:189], v[82:85]
	v_mfma_f32_16x16x32_bf16 v[74:77], v[178:181], v[186:189], v[74:77]
	v_mfma_f32_16x16x32_bf16 v[70:73], v[162:165], v[194:197], v[70:73]
	v_mfma_f32_16x16x32_bf16 v[62:65], v[178:181], v[194:197], v[62:65]
	v_mfma_f32_16x16x32_bf16 v[54:57], v[162:165], v[202:205], v[54:57]
	v_mfma_f32_16x16x32_bf16 v[46:49], v[178:181], v[202:205], v[46:49]
	v_mfma_f32_16x16x32_bf16 v[38:41], v[162:165], v[210:213], v[38:41]
	v_mfma_f32_16x16x32_bf16 v[34:37], v[178:181], v[210:213], v[34:37]
	s_barrier
	s_add_i32 s59, s59, s44
	v_lshl_add_u64 v[214:215], v[214:215], 0, s[98:99]
	s_mov_b32 m0, s59
	ds_read_b128 v[182:185], v173 offset:49152
	ds_read_b128 v[186:189], v173 offset:50176
	ds_read_b128 v[190:193], v173 offset:51200
	ds_read_b128 v[194:197], v173 offset:52224
	ds_read_b128 v[198:201], v173 offset:53248
	ds_read_b128 v[202:205], v173 offset:54272
	ds_read_b128 v[206:209], v173 offset:55296
	ds_read_b128 v[210:213], v173 offset:56320
	global_load_lds_dwordx4 v[214:215], off
	s_add_i32 m0, s59, 0x2000
	s_add_u32 s26, s26, 0x40080
	v_lshl_add_u64 v[214:215], v[216:217], 0, s[98:99]
	s_addc_u32 s27, s27, 0
	s_add_i32 s59, s62, s44
	global_load_lds_dwordx4 v[214:215], off
	v_lshl_add_u64 v[214:215], s[26:27], 0, v[132:133]
	s_mov_b32 m0, s59
	s_nop 0
	global_load_lds_dwordx4 v[214:215], off
	v_lshl_add_u64 v[214:215], s[26:27], 0, v[136:137]
	s_add_i32 m0, s59, 0x2000
	s_nop 0
	global_load_lds_dwordx4 v[214:215], off
	v_lshl_add_u64 v[214:215], v[218:219], 0, s[98:99]
	s_mov_b32 m0, s52
	s_nop 0
	global_load_lds_dwordx4 v[214:215], off
	v_lshl_add_u64 v[214:215], v[220:221], 0, s[98:99]
	s_mov_b32 m0, s53
	s_nop 0
	global_load_lds_dwordx4 v[214:215], off
	s_waitcnt vmcnt(8)
	s_waitcnt lgkmcnt(0)
	s_barrier
	s_waitcnt lgkmcnt(0)
	v_mfma_f32_16x16x32_bf16 v[94:97], v[142:145], v[182:185], v[94:97]
	v_mfma_f32_16x16x32_bf16 v[90:93], v[150:153], v[182:185], v[90:93]
	v_mfma_f32_16x16x32_bf16 v[86:89], v[142:145], v[190:193], v[86:89]
	v_mfma_f32_16x16x32_bf16 v[78:81], v[150:153], v[190:193], v[78:81]
	v_mfma_f32_16x16x32_bf16 v[66:69], v[142:145], v[198:201], v[66:69]
	v_mfma_f32_16x16x32_bf16 v[58:61], v[150:153], v[198:201], v[58:61]
	v_mfma_f32_16x16x32_bf16 v[50:53], v[142:145], v[206:209], v[50:53]
	v_mfma_f32_16x16x32_bf16 v[42:45], v[150:153], v[206:209], v[42:45]
	v_mfma_f32_16x16x32_bf16 v[94:97], v[146:149], v[186:189], v[94:97]
	v_mfma_f32_16x16x32_bf16 v[90:93], v[154:157], v[186:189], v[90:93]
	v_mfma_f32_16x16x32_bf16 v[86:89], v[146:149], v[194:197], v[86:89]
	v_mfma_f32_16x16x32_bf16 v[78:81], v[154:157], v[194:197], v[78:81]
	v_mfma_f32_16x16x32_bf16 v[66:69], v[146:149], v[202:205], v[66:69]
	v_mfma_f32_16x16x32_bf16 v[58:61], v[154:157], v[202:205], v[58:61]
	v_mfma_f32_16x16x32_bf16 v[50:53], v[146:149], v[210:213], v[50:53]
	v_mfma_f32_16x16x32_bf16 v[42:45], v[154:157], v[210:213], v[42:45]
	v_mfma_f32_16x16x32_bf16 v[30:33], v[158:161], v[182:185], v[30:33]
	v_mfma_f32_16x16x32_bf16 v[26:29], v[174:177], v[182:185], v[26:29]
	v_mfma_f32_16x16x32_bf16 v[22:25], v[158:161], v[190:193], v[22:25]
	v_mfma_f32_16x16x32_bf16 v[18:21], v[174:177], v[190:193], v[18:21]
	v_mfma_f32_16x16x32_bf16 v[14:17], v[158:161], v[198:201], v[14:17]
	v_mfma_f32_16x16x32_bf16 v[10:13], v[174:177], v[198:201], v[10:13]
	v_mfma_f32_16x16x32_bf16 v[6:9], v[158:161], v[206:209], v[6:9]
	v_mfma_f32_16x16x32_bf16 v[2:5], v[174:177], v[206:209], v[2:5]
	v_mfma_f32_16x16x32_bf16 v[30:33], v[162:165], v[186:189], v[30:33]
	v_mfma_f32_16x16x32_bf16 v[26:29], v[178:181], v[186:189], v[26:29]
	v_mfma_f32_16x16x32_bf16 v[22:25], v[162:165], v[194:197], v[22:25]
	v_mfma_f32_16x16x32_bf16 v[18:21], v[178:181], v[194:197], v[18:21]
	v_mfma_f32_16x16x32_bf16 v[14:17], v[162:165], v[202:205], v[14:17]
	v_mfma_f32_16x16x32_bf16 v[10:13], v[178:181], v[202:205], v[10:13]
	v_mfma_f32_16x16x32_bf16 v[6:9], v[162:165], v[210:213], v[6:9]
	v_mfma_f32_16x16x32_bf16 v[2:5], v[178:181], v[210:213], v[2:5]
	s_barrier
	s_add_i32 s58, s58, 2
	s_add_u32 s40, s40, 0x100
	s_addc_u32 s41, s41, 0
	s_add_u32 s56, s56, 0x100
	s_addc_u32 s57, s57, 0
	s_cmp_gt_u32 s58, 13
	s_cbranch_scc1 .Lpeel_done_160
.LBB0_160:
	s_add_u32 s26, s40, 0xfffc0080
	s_addc_u32 s27, s41, -1
	s_add_i32 s59, 0, 0x10000
	s_cmp_eq_u32 s58, 12
	s_cselect_b32 vcc_hi, s29, s27
	s_cselect_b32 vcc_lo, s43, s26
	v_add_u32_e32 v0, s59, v167
	s_cselect_b32 s27, s21, s57
	s_cselect_b32 s26, s55, s56
	s_add_i32 s62, 0, 0x14000
	ds_read_b128 v[142:145], v0
	ds_read_b128 v[146:149], v0 offset:1024
	ds_read_b128 v[150:153], v0 offset:2048
	ds_read_b128 v[154:157], v0 offset:3072
	v_add_u32_e32 v0, s62, v167
	ds_read_b128 v[158:161], v0
	ds_read_b128 v[162:165], v0 offset:1024
	ds_read_b128 v[174:177], v0 offset:2048
	ds_read_b128 v[178:181], v0 offset:3072
	v_lshl_add_u64 v[214:215], s[40:41], 0, v[138:139]
	s_add_i32 m0, s23, 0xc000
	ds_read_b128 v[182:185], v173
	ds_read_b128 v[186:189], v173 offset:1024
	ds_read_b128 v[190:193], v173 offset:2048
	ds_read_b128 v[194:197], v173 offset:3072
	ds_read_b128 v[198:201], v173 offset:4096
	ds_read_b128 v[202:205], v173 offset:5120
	ds_read_b128 v[206:209], v173 offset:6144
	ds_read_b128 v[210:213], v173 offset:7168
	global_load_lds_dwordx4 v[214:215], off
	v_lshl_add_u64 v[214:215], s[40:41], 0, v[140:141]
	s_add_i32 m0, s23, 0xe000
	s_nop 0
	global_load_lds_dwordx4 v[214:215], off
	s_waitcnt vmcnt(8)
	s_waitcnt lgkmcnt(0)
	s_barrier
	s_waitcnt lgkmcnt(0)
	v_mfma_f32_16x16x32_bf16 v[126:129], v[142:145], v[182:185], v[126:129]
	v_mfma_f32_16x16x32_bf16 v[122:125], v[150:153], v[182:185], v[122:125]
	v_mfma_f32_16x16x32_bf16 v[118:121], v[142:145], v[190:193], v[118:121]
	v_mfma_f32_16x16x32_bf16 v[114:117], v[150:153], v[190:193], v[114:117]
	v_mfma_f32_16x16x32_bf16 v[110:113], v[142:145], v[198:201], v[110:113]
	v_mfma_f32_16x16x32_bf16 v[106:109], v[150:153], v[198:201], v[106:109]
	v_mfma_f32_16x16x32_bf16 v[102:105], v[142:145], v[206:209], v[102:105]
	v_mfma_f32_16x16x32_bf16 v[98:101], v[150:153], v[206:209], v[98:101]
	v_mfma_f32_16x16x32_bf16 v[126:129], v[146:149], v[186:189], v[126:129]
	v_mfma_f32_16x16x32_bf16 v[122:125], v[154:157], v[186:189], v[122:125]
	v_mfma_f32_16x16x32_bf16 v[118:121], v[146:149], v[194:197], v[118:121]
	v_mfma_f32_16x16x32_bf16 v[114:117], v[154:157], v[194:197], v[114:117]
	v_mfma_f32_16x16x32_bf16 v[110:113], v[146:149], v[202:205], v[110:113]
	v_mfma_f32_16x16x32_bf16 v[106:109], v[154:157], v[202:205], v[106:109]
	v_mfma_f32_16x16x32_bf16 v[102:105], v[146:149], v[210:213], v[102:105]
	v_mfma_f32_16x16x32_bf16 v[98:101], v[154:157], v[210:213], v[98:101]
	v_mfma_f32_16x16x32_bf16 v[82:85], v[158:161], v[182:185], v[82:85]
	v_mfma_f32_16x16x32_bf16 v[74:77], v[174:177], v[182:185], v[74:77]
	v_mfma_f32_16x16x32_bf16 v[70:73], v[158:161], v[190:193], v[70:73]
	v_mfma_f32_16x16x32_bf16 v[62:65], v[174:177], v[190:193], v[62:65]
	v_mfma_f32_16x16x32_bf16 v[54:57], v[158:161], v[198:201], v[54:57]
	v_mfma_f32_16x16x32_bf16 v[46:49], v[174:177], v[198:201], v[46:49]
	v_mfma_f32_16x16x32_bf16 v[38:41], v[158:161], v[206:209], v[38:41]
	v_mfma_f32_16x16x32_bf16 v[34:37], v[174:177], v[206:209], v[34:37]
	v_mfma_f32_16x16x32_bf16 v[82:85], v[162:165], v[186:189], v[82:85]
	v_mfma_f32_16x16x32_bf16 v[74:77], v[178:181], v[186:189], v[74:77]
	v_mfma_f32_16x16x32_bf16 v[70:73], v[162:165], v[194:197], v[70:73]
	v_mfma_f32_16x16x32_bf16 v[62:65], v[178:181], v[194:197], v[62:65]
	v_mfma_f32_16x16x32_bf16 v[54:57], v[162:165], v[202:205], v[54:57]
	v_mfma_f32_16x16x32_bf16 v[46:49], v[178:181], v[202:205], v[46:49]
	v_mfma_f32_16x16x32_bf16 v[38:41], v[162:165], v[210:213], v[38:41]
	v_mfma_f32_16x16x32_bf16 v[34:37], v[178:181], v[210:213], v[34:37]
	s_barrier
	s_add_i32 s59, s59, s44
	v_lshl_add_u64 v[214:215], s[26:27], 0, v[132:133]
	s_mov_b32 m0, s59
	ds_read_b128 v[182:185], v173 offset:16384
	ds_read_b128 v[186:189], v173 offset:17408
	ds_read_b128 v[190:193], v173 offset:18432
	ds_read_b128 v[194:197], v173 offset:19456
	ds_read_b128 v[198:201], v173 offset:20480
	ds_read_b128 v[202:205], v173 offset:21504
	ds_read_b128 v[206:209], v173 offset:22528
	ds_read_b128 v[210:213], v173 offset:23552
	global_load_lds_dwordx4 v[214:215], off
	s_add_i32 m0, s59, 0x2000
	s_add_u32 s60, s26, 0x40000
	v_lshl_add_u64 v[216:217], s[26:27], 0, v[136:137]
	s_addc_u32 s61, s27, 0
	s_add_i32 s59, s62, s44
	global_load_lds_dwordx4 v[216:217], off
	v_lshl_add_u64 v[218:219], s[60:61], 0, v[132:133]
	s_mov_b32 m0, s59
	v_lshl_add_u64 v[220:221], vcc, 0, v[134:135]
	global_load_lds_dwordx4 v[218:219], off
	v_lshl_add_u64 v[218:219], s[60:61], 0, v[136:137]
	s_add_i32 m0, s59, 0x2000
	s_nop 0
	global_load_lds_dwordx4 v[218:219], off
	v_lshl_add_u64 v[218:219], vcc, 0, v[130:131]
	s_mov_b32 m0, s23
	s_nop 0
	global_load_lds_dwordx4 v[218:219], off
	s_mov_b32 m0, s45
	s_nop 0
	global_load_lds_dwordx4 v[220:221], off
	s_waitcnt vmcnt(8)
	s_waitcnt lgkmcnt(0)
	s_barrier
	s_waitcnt lgkmcnt(0)
	v_mfma_f32_16x16x32_bf16 v[94:97], v[142:145], v[182:185], v[94:97]
	v_mfma_f32_16x16x32_bf16 v[90:93], v[150:153], v[182:185], v[90:93]
	v_mfma_f32_16x16x32_bf16 v[86:89], v[142:145], v[190:193], v[86:89]
	v_mfma_f32_16x16x32_bf16 v[78:81], v[150:153], v[190:193], v[78:81]
	v_mfma_f32_16x16x32_bf16 v[66:69], v[142:145], v[198:201], v[66:69]
	v_mfma_f32_16x16x32_bf16 v[58:61], v[150:153], v[198:201], v[58:61]
	v_mfma_f32_16x16x32_bf16 v[50:53], v[142:145], v[206:209], v[50:53]
	v_mfma_f32_16x16x32_bf16 v[42:45], v[150:153], v[206:209], v[42:45]
	v_mfma_f32_16x16x32_bf16 v[94:97], v[146:149], v[186:189], v[94:97]
	v_mfma_f32_16x16x32_bf16 v[90:93], v[154:157], v[186:189], v[90:93]
	v_mfma_f32_16x16x32_bf16 v[86:89], v[146:149], v[194:197], v[86:89]
	v_mfma_f32_16x16x32_bf16 v[78:81], v[154:157], v[194:197], v[78:81]
	v_mfma_f32_16x16x32_bf16 v[66:69], v[146:149], v[202:205], v[66:69]
	v_mfma_f32_16x16x32_bf16 v[58:61], v[154:157], v[202:205], v[58:61]
	v_mfma_f32_16x16x32_bf16 v[50:53], v[146:149], v[210:213], v[50:53]
	v_mfma_f32_16x16x32_bf16 v[42:45], v[154:157], v[210:213], v[42:45]
	v_mfma_f32_16x16x32_bf16 v[30:33], v[158:161], v[182:185], v[30:33]
	v_mfma_f32_16x16x32_bf16 v[26:29], v[174:177], v[182:185], v[26:29]
	v_mfma_f32_16x16x32_bf16 v[22:25], v[158:161], v[190:193], v[22:25]
	v_mfma_f32_16x16x32_bf16 v[18:21], v[174:177], v[190:193], v[18:21]
	v_mfma_f32_16x16x32_bf16 v[14:17], v[158:161], v[198:201], v[14:17]
	v_mfma_f32_16x16x32_bf16 v[10:13], v[174:177], v[198:201], v[10:13]
	v_mfma_f32_16x16x32_bf16 v[6:9], v[158:161], v[206:209], v[6:9]
	v_mfma_f32_16x16x32_bf16 v[2:5], v[174:177], v[206:209], v[2:5]
	v_mfma_f32_16x16x32_bf16 v[30:33], v[162:165], v[186:189], v[30:33]
	v_mfma_f32_16x16x32_bf16 v[26:29], v[178:181], v[186:189], v[26:29]
	v_mfma_f32_16x16x32_bf16 v[22:25], v[162:165], v[194:197], v[22:25]
	v_mfma_f32_16x16x32_bf16 v[18:21], v[178:181], v[194:197], v[18:21]
	v_mfma_f32_16x16x32_bf16 v[14:17], v[162:165], v[202:205], v[14:17]
	v_mfma_f32_16x16x32_bf16 v[10:13], v[178:181], v[202:205], v[10:13]
	v_mfma_f32_16x16x32_bf16 v[6:9], v[162:165], v[210:213], v[6:9]
	v_mfma_f32_16x16x32_bf16 v[2:5], v[178:181], v[210:213], v[2:5]
	s_barrier
	s_add_i32 s59, 0, 0x18000
	v_add_u32_e32 v0, s59, v167
	s_add_i32 s62, 0, 0x1c000
	ds_read_b128 v[142:145], v0
	ds_read_b128 v[146:149], v0 offset:1024
	ds_read_b128 v[150:153], v0 offset:2048
	ds_read_b128 v[154:157], v0 offset:3072
	v_add_u32_e32 v0, s62, v167
	ds_read_b128 v[158:161], v0
	ds_read_b128 v[162:165], v0 offset:1024
	ds_read_b128 v[174:177], v0 offset:2048
	ds_read_b128 v[178:181], v0 offset:3072
	s_add_u32 s60, vcc_lo, 0x40000
	s_addc_u32 s61, vcc_hi, 0
	s_mov_b32 m0, s47
	v_lshl_add_u64 v[222:223], s[60:61], 0, v[130:131]
	ds_read_b128 v[182:185], v173 offset:32768
	ds_read_b128 v[186:189], v173 offset:33792
	ds_read_b128 v[190:193], v173 offset:34816
	ds_read_b128 v[194:197], v173 offset:35840
	ds_read_b128 v[198:201], v173 offset:36864
	ds_read_b128 v[202:205], v173 offset:37888
	ds_read_b128 v[206:209], v173 offset:38912
	ds_read_b128 v[210:213], v173 offset:39936
	global_load_lds_dwordx4 v[222:223], off
	v_lshl_add_u64 v[222:223], s[60:61], 0, v[134:135]
	s_mov_b32 m0, s49
	s_nop 0
	global_load_lds_dwordx4 v[222:223], off
	s_waitcnt vmcnt(8)
	s_waitcnt lgkmcnt(0)
	s_barrier
	s_waitcnt lgkmcnt(0)
	v_mfma_f32_16x16x32_bf16 v[126:129], v[142:145], v[182:185], v[126:129]
	v_mfma_f32_16x16x32_bf16 v[122:125], v[150:153], v[182:185], v[122:125]
	v_mfma_f32_16x16x32_bf16 v[118:121], v[142:145], v[190:193], v[118:121]
	v_mfma_f32_16x16x32_bf16 v[114:117], v[150:153], v[190:193], v[114:117]
	v_mfma_f32_16x16x32_bf16 v[110:113], v[142:145], v[198:201], v[110:113]
	v_mfma_f32_16x16x32_bf16 v[106:109], v[150:153], v[198:201], v[106:109]
	v_mfma_f32_16x16x32_bf16 v[102:105], v[142:145], v[206:209], v[102:105]
	v_mfma_f32_16x16x32_bf16 v[98:101], v[150:153], v[206:209], v[98:101]
	v_mfma_f32_16x16x32_bf16 v[126:129], v[146:149], v[186:189], v[126:129]
	v_mfma_f32_16x16x32_bf16 v[122:125], v[154:157], v[186:189], v[122:125]
	v_mfma_f32_16x16x32_bf16 v[118:121], v[146:149], v[194:197], v[118:121]
	v_mfma_f32_16x16x32_bf16 v[114:117], v[154:157], v[194:197], v[114:117]
	v_mfma_f32_16x16x32_bf16 v[110:113], v[146:149], v[202:205], v[110:113]
	v_mfma_f32_16x16x32_bf16 v[106:109], v[154:157], v[202:205], v[106:109]
	v_mfma_f32_16x16x32_bf16 v[102:105], v[146:149], v[210:213], v[102:105]
	v_mfma_f32_16x16x32_bf16 v[98:101], v[154:157], v[210:213], v[98:101]
	v_mfma_f32_16x16x32_bf16 v[82:85], v[158:161], v[182:185], v[82:85]
	v_mfma_f32_16x16x32_bf16 v[74:77], v[174:177], v[182:185], v[74:77]
	v_mfma_f32_16x16x32_bf16 v[70:73], v[158:161], v[190:193], v[70:73]
	v_mfma_f32_16x16x32_bf16 v[62:65], v[174:177], v[190:193], v[62:65]
	v_mfma_f32_16x16x32_bf16 v[54:57], v[158:161], v[198:201], v[54:57]
	v_mfma_f32_16x16x32_bf16 v[46:49], v[174:177], v[198:201], v[46:49]
	v_mfma_f32_16x16x32_bf16 v[38:41], v[158:161], v[206:209], v[38:41]
	v_mfma_f32_16x16x32_bf16 v[34:37], v[174:177], v[206:209], v[34:37]
	v_mfma_f32_16x16x32_bf16 v[82:85], v[162:165], v[186:189], v[82:85]
	v_mfma_f32_16x16x32_bf16 v[74:77], v[178:181], v[186:189], v[74:77]
	v_mfma_f32_16x16x32_bf16 v[70:73], v[162:165], v[194:197], v[70:73]
	v_mfma_f32_16x16x32_bf16 v[62:65], v[178:181], v[194:197], v[62:65]
	v_mfma_f32_16x16x32_bf16 v[54:57], v[162:165], v[202:205], v[54:57]
	v_mfma_f32_16x16x32_bf16 v[46:49], v[178:181], v[202:205], v[46:49]
	v_mfma_f32_16x16x32_bf16 v[38:41], v[162:165], v[210:213], v[38:41]
	v_mfma_f32_16x16x32_bf16 v[34:37], v[178:181], v[210:213], v[34:37]
	s_barrier
	s_add_i32 s59, s59, s44
	v_lshl_add_u64 v[214:215], v[214:215], 0, s[98:99]
	s_mov_b32 m0, s59
	ds_read_b128 v[182:185], v173 offset:49152
	ds_read_b128 v[186:189], v173 offset:50176
	ds_read_b128 v[190:193], v173 offset:51200
	ds_read_b128 v[194:197], v173 offset:52224
	ds_read_b128 v[198:201], v173 offset:53248
	ds_read_b128 v[202:205], v173 offset:54272
	ds_read_b128 v[206:209], v173 offset:55296
	ds_read_b128 v[210:213], v173 offset:56320
	global_load_lds_dwordx4 v[214:215], off
	s_add_i32 m0, s59, 0x2000
	s_add_u32 s26, s26, 0x40080
	v_lshl_add_u64 v[214:215], v[216:217], 0, s[98:99]
	s_addc_u32 s27, s27, 0
	s_add_i32 s59, s62, s44
	global_load_lds_dwordx4 v[214:215], off
	v_lshl_add_u64 v[214:215], s[26:27], 0, v[132:133]
	s_mov_b32 m0, s59
	s_nop 0
	global_load_lds_dwordx4 v[214:215], off
	v_lshl_add_u64 v[214:215], s[26:27], 0, v[136:137]
	s_add_i32 m0, s59, 0x2000
	s_nop 0
	global_load_lds_dwordx4 v[214:215], off
	v_lshl_add_u64 v[214:215], v[218:219], 0, s[98:99]
	s_mov_b32 m0, s52
	s_nop 0
	global_load_lds_dwordx4 v[214:215], off
	v_lshl_add_u64 v[214:215], v[220:221], 0, s[98:99]
	s_mov_b32 m0, s53
	s_nop 0
	global_load_lds_dwordx4 v[214:215], off
	s_waitcnt vmcnt(8)
	s_waitcnt lgkmcnt(0)
	s_barrier
	s_waitcnt lgkmcnt(0)
	v_mfma_f32_16x16x32_bf16 v[94:97], v[142:145], v[182:185], v[94:97]
	v_mfma_f32_16x16x32_bf16 v[90:93], v[150:153], v[182:185], v[90:93]
	v_mfma_f32_16x16x32_bf16 v[86:89], v[142:145], v[190:193], v[86:89]
	v_mfma_f32_16x16x32_bf16 v[78:81], v[150:153], v[190:193], v[78:81]
	v_mfma_f32_16x16x32_bf16 v[66:69], v[142:145], v[198:201], v[66:69]
	v_mfma_f32_16x16x32_bf16 v[58:61], v[150:153], v[198:201], v[58:61]
	v_mfma_f32_16x16x32_bf16 v[50:53], v[142:145], v[206:209], v[50:53]
	v_mfma_f32_16x16x32_bf16 v[42:45], v[150:153], v[206:209], v[42:45]
	v_mfma_f32_16x16x32_bf16 v[94:97], v[146:149], v[186:189], v[94:97]
	v_mfma_f32_16x16x32_bf16 v[90:93], v[154:157], v[186:189], v[90:93]
	v_mfma_f32_16x16x32_bf16 v[86:89], v[146:149], v[194:197], v[86:89]
	v_mfma_f32_16x16x32_bf16 v[78:81], v[154:157], v[194:197], v[78:81]
	v_mfma_f32_16x16x32_bf16 v[66:69], v[146:149], v[202:205], v[66:69]
	v_mfma_f32_16x16x32_bf16 v[58:61], v[154:157], v[202:205], v[58:61]
	v_mfma_f32_16x16x32_bf16 v[50:53], v[146:149], v[210:213], v[50:53]
	v_mfma_f32_16x16x32_bf16 v[42:45], v[154:157], v[210:213], v[42:45]
	v_mfma_f32_16x16x32_bf16 v[30:33], v[158:161], v[182:185], v[30:33]
	v_mfma_f32_16x16x32_bf16 v[26:29], v[174:177], v[182:185], v[26:29]
	v_mfma_f32_16x16x32_bf16 v[22:25], v[158:161], v[190:193], v[22:25]
	v_mfma_f32_16x16x32_bf16 v[18:21], v[174:177], v[190:193], v[18:21]
	v_mfma_f32_16x16x32_bf16 v[14:17], v[158:161], v[198:201], v[14:17]
	v_mfma_f32_16x16x32_bf16 v[10:13], v[174:177], v[198:201], v[10:13]
	v_mfma_f32_16x16x32_bf16 v[6:9], v[158:161], v[206:209], v[6:9]
	v_mfma_f32_16x16x32_bf16 v[2:5], v[174:177], v[206:209], v[2:5]
	v_mfma_f32_16x16x32_bf16 v[30:33], v[162:165], v[186:189], v[30:33]
	v_mfma_f32_16x16x32_bf16 v[26:29], v[178:181], v[186:189], v[26:29]
	v_mfma_f32_16x16x32_bf16 v[22:25], v[162:165], v[194:197], v[22:25]
	v_mfma_f32_16x16x32_bf16 v[18:21], v[178:181], v[194:197], v[18:21]
	v_mfma_f32_16x16x32_bf16 v[14:17], v[162:165], v[202:205], v[14:17]
	v_mfma_f32_16x16x32_bf16 v[10:13], v[178:181], v[202:205], v[10:13]
	v_mfma_f32_16x16x32_bf16 v[6:9], v[162:165], v[210:213], v[6:9]
	v_mfma_f32_16x16x32_bf16 v[2:5], v[178:181], v[210:213], v[2:5]
	s_barrier
	s_add_i32 s58, s58, 2
	s_add_u32 s40, s40, 0x100
	s_addc_u32 s41, s41, 0
	s_add_u32 s56, s56, 0x100
	s_addc_u32 s57, s57, 0
	s_cmp_gt_u32 s58, 13
	s_cbranch_scc0 .LBB0_160

.LBB0_216:
	s_add_i32 s13, s61, -2
	s_add_u32 s28, s28, 0x80
	s_addc_u32 s29, s29, 0
	s_add_u32 s23, s40, 0x100
	s_addc_u32 s40, s41, 0
	s_mov_b32 s30, 0
	s_add_i32 s41, s30, 2
	s_add_u32 vcc_lo, s28, 0x80
	s_addc_u32 s31, s29, 0
	s_add_i32 s62, 0, 0x10000
	s_cmp_eq_u32 s13, s30
	s_cselect_b32 s31, s25, s31
	s_cselect_b32 s30, s24, vcc_lo
	v_add_u32_e32 v145, s62, v175
	s_cselect_b32 vcc_hi, s27, s40
	s_cselect_b32 vcc_lo, s26, s23
	s_add_i32 s63, 0, 0x14000
	ds_read_b128 v[130:133], v145
	ds_read_b128 v[134:137], v145 offset:1024
	ds_read_b128 v[152:155], v145 offset:2048
	ds_read_b128 v[156:159], v145 offset:3072
	v_add_u32_e32 v145, s63, v175
	ds_read_b128 v[160:163], v145
	ds_read_b128 v[164:167], v145 offset:1024
	ds_read_b128 v[168:171], v145 offset:2048
	ds_read_b128 v[186:189], v145 offset:3072
	v_lshl_add_u64 v[172:173], s[28:29], 0, v[148:149]
	s_add_i32 m0, s93, 0xc000
	ds_read_b128 v[190:193], v184
	ds_read_b128 v[194:197], v184 offset:1024
	ds_read_b128 v[198:201], v184 offset:2048
	ds_read_b128 v[202:205], v184 offset:3072
	ds_read_b128 v[206:209], v184 offset:4096
	ds_read_b128 v[210:213], v184 offset:5120
	ds_read_b128 v[214:217], v184 offset:6144
	ds_read_b128 v[218:221], v184 offset:7168
	global_load_lds_dwordx4 v[172:173], off
	v_lshl_add_u64 v[172:173], s[28:29], 0, v[150:151]
	s_add_i32 m0, s93, 0xe000
	s_nop 0
	global_load_lds_dwordx4 v[172:173], off
	s_waitcnt vmcnt(8)
	s_waitcnt lgkmcnt(0)
	s_barrier
	s_waitcnt lgkmcnt(0)
	v_mfma_f32_16x16x32_bf16 v[126:129], v[130:133], v[190:193], 0
	v_mfma_f32_16x16x32_bf16 v[122:125], v[152:155], v[190:193], 0
	v_mfma_f32_16x16x32_bf16 v[110:113], v[130:133], v[198:201], 0
	v_mfma_f32_16x16x32_bf16 v[106:109], v[152:155], v[198:201], 0
	v_mfma_f32_16x16x32_bf16 v[94:97], v[130:133], v[206:209], 0
	v_mfma_f32_16x16x32_bf16 v[90:93], v[152:155], v[206:209], 0
	v_mfma_f32_16x16x32_bf16 v[78:81], v[130:133], v[214:217], 0
	v_mfma_f32_16x16x32_bf16 v[74:77], v[152:155], v[214:217], 0
	v_mfma_f32_16x16x32_bf16 v[126:129], v[134:137], v[194:197], v[126:129]
	v_mfma_f32_16x16x32_bf16 v[122:125], v[156:159], v[194:197], v[122:125]
	v_mfma_f32_16x16x32_bf16 v[110:113], v[134:137], v[202:205], v[110:113]
	v_mfma_f32_16x16x32_bf16 v[106:109], v[156:159], v[202:205], v[106:109]
	v_mfma_f32_16x16x32_bf16 v[94:97], v[134:137], v[210:213], v[94:97]
	v_mfma_f32_16x16x32_bf16 v[90:93], v[156:159], v[210:213], v[90:93]
	v_mfma_f32_16x16x32_bf16 v[78:81], v[134:137], v[218:221], v[78:81]
	v_mfma_f32_16x16x32_bf16 v[74:77], v[156:159], v[218:221], v[74:77]
	v_mfma_f32_16x16x32_bf16 v[118:121], v[160:163], v[190:193], 0
	v_mfma_f32_16x16x32_bf16 v[114:117], v[168:171], v[190:193], 0
	v_mfma_f32_16x16x32_bf16 v[102:105], v[160:163], v[198:201], 0
	v_mfma_f32_16x16x32_bf16 v[98:101], v[168:171], v[198:201], 0
	v_mfma_f32_16x16x32_bf16 v[86:89], v[160:163], v[206:209], 0
	v_mfma_f32_16x16x32_bf16 v[82:85], v[168:171], v[206:209], 0
	v_mfma_f32_16x16x32_bf16 v[70:73], v[160:163], v[214:217], 0
	v_mfma_f32_16x16x32_bf16 v[66:69], v[168:171], v[214:217], 0
	v_mfma_f32_16x16x32_bf16 v[118:121], v[164:167], v[194:197], v[118:121]
	v_mfma_f32_16x16x32_bf16 v[114:117], v[186:189], v[194:197], v[114:117]
	v_mfma_f32_16x16x32_bf16 v[102:105], v[164:167], v[202:205], v[102:105]
	v_mfma_f32_16x16x32_bf16 v[98:101], v[186:189], v[202:205], v[98:101]
	v_mfma_f32_16x16x32_bf16 v[86:89], v[164:167], v[210:213], v[86:89]
	v_mfma_f32_16x16x32_bf16 v[82:85], v[186:189], v[210:213], v[82:85]
	v_mfma_f32_16x16x32_bf16 v[70:73], v[164:167], v[218:221], v[70:73]
	v_mfma_f32_16x16x32_bf16 v[66:69], v[186:189], v[218:221], v[66:69]
	s_barrier
	s_add_i32 s62, s62, s49
	v_lshl_add_u64 v[172:173], vcc, 0, v[0:1]
	s_mov_b32 m0, s62
	ds_read_b128 v[190:193], v184 offset:16384
	ds_read_b128 v[194:197], v184 offset:17408
	ds_read_b128 v[198:201], v184 offset:18432
	ds_read_b128 v[202:205], v184 offset:19456
	ds_read_b128 v[206:209], v184 offset:20480
	ds_read_b128 v[210:213], v184 offset:21504
	ds_read_b128 v[214:217], v184 offset:22528
	ds_read_b128 v[218:221], v184 offset:23552
	global_load_lds_dwordx4 v[172:173], off
	s_add_i32 m0, s62, 0x2000
	v_lshl_add_u64 v[222:223], vcc, 0, v[142:143]
	s_add_u32 vcc_lo, vcc_lo, s96
	s_addc_u32 vcc_hi, vcc_hi, 0
	s_add_i32 s62, s63, s49
	global_load_lds_dwordx4 v[222:223], off
	v_lshl_add_u64 v[236:237], vcc, 0, v[0:1]
	s_mov_b32 m0, s62
	v_lshl_add_u64 v[238:239], vcc, 0, v[142:143]
	global_load_lds_dwordx4 v[236:237], off
	s_add_i32 m0, s62, 0x2000
	v_lshl_add_u64 v[240:241], s[30:31], 0, v[138:139]
	global_load_lds_dwordx4 v[238:239], off
	s_mov_b32 m0, s93
	v_lshl_add_u64 v[242:243], s[30:31], 0, v[140:141]
	global_load_lds_dwordx4 v[240:241], off
	s_mov_b32 m0, s88
	s_nop 0
	global_load_lds_dwordx4 v[242:243], off
	s_waitcnt vmcnt(8)
	s_waitcnt lgkmcnt(0)
	s_barrier
	s_waitcnt lgkmcnt(0)
	v_mfma_f32_16x16x32_bf16 v[62:65], v[130:133], v[190:193], 0
	v_mfma_f32_16x16x32_bf16 v[58:61], v[152:155], v[190:193], 0
	v_mfma_f32_16x16x32_bf16 v[46:49], v[130:133], v[198:201], 0
	v_mfma_f32_16x16x32_bf16 v[42:45], v[152:155], v[198:201], 0
	v_mfma_f32_16x16x32_bf16 v[30:33], v[130:133], v[206:209], 0
	v_mfma_f32_16x16x32_bf16 v[26:29], v[152:155], v[206:209], 0
	v_mfma_f32_16x16x32_bf16 v[14:17], v[130:133], v[214:217], 0
	v_mfma_f32_16x16x32_bf16 v[10:13], v[152:155], v[214:217], 0
	v_mfma_f32_16x16x32_bf16 v[62:65], v[134:137], v[194:197], v[62:65]
	v_mfma_f32_16x16x32_bf16 v[58:61], v[156:159], v[194:197], v[58:61]
	v_mfma_f32_16x16x32_bf16 v[46:49], v[134:137], v[202:205], v[46:49]
	v_mfma_f32_16x16x32_bf16 v[42:45], v[156:159], v[202:205], v[42:45]
	v_mfma_f32_16x16x32_bf16 v[30:33], v[134:137], v[210:213], v[30:33]
	v_mfma_f32_16x16x32_bf16 v[26:29], v[156:159], v[210:213], v[26:29]
	v_mfma_f32_16x16x32_bf16 v[14:17], v[134:137], v[218:221], v[14:17]
	v_mfma_f32_16x16x32_bf16 v[10:13], v[156:159], v[218:221], v[10:13]
	v_mfma_f32_16x16x32_bf16 v[54:57], v[160:163], v[190:193], 0
	v_mfma_f32_16x16x32_bf16 v[50:53], v[168:171], v[190:193], 0
	v_mfma_f32_16x16x32_bf16 v[38:41], v[160:163], v[198:201], 0
	v_mfma_f32_16x16x32_bf16 v[34:37], v[168:171], v[198:201], 0
	v_mfma_f32_16x16x32_bf16 v[22:25], v[160:163], v[206:209], 0
	v_mfma_f32_16x16x32_bf16 v[18:21], v[168:171], v[206:209], 0
	v_mfma_f32_16x16x32_bf16 v[6:9], v[160:163], v[214:217], 0
	v_mfma_f32_16x16x32_bf16 v[2:5], v[168:171], v[214:217], 0
	v_mfma_f32_16x16x32_bf16 v[54:57], v[164:167], v[194:197], v[54:57]
	v_mfma_f32_16x16x32_bf16 v[50:53], v[186:189], v[194:197], v[50:53]
	v_mfma_f32_16x16x32_bf16 v[38:41], v[164:167], v[202:205], v[38:41]
	v_mfma_f32_16x16x32_bf16 v[34:37], v[186:189], v[202:205], v[34:37]
	v_mfma_f32_16x16x32_bf16 v[22:25], v[164:167], v[210:213], v[22:25]
	v_mfma_f32_16x16x32_bf16 v[18:21], v[186:189], v[210:213], v[18:21]
	v_mfma_f32_16x16x32_bf16 v[6:9], v[164:167], v[218:221], v[6:9]
	v_mfma_f32_16x16x32_bf16 v[2:5], v[186:189], v[218:221], v[2:5]
	s_barrier
	s_add_i32 s62, 0, 0x18000
	v_add_u32_e32 v145, s62, v175
	s_add_i32 s63, 0, 0x1c000
	ds_read_b128 v[130:133], v145
	ds_read_b128 v[134:137], v145 offset:1024
	ds_read_b128 v[152:155], v145 offset:2048
	ds_read_b128 v[156:159], v145 offset:3072
	v_add_u32_e32 v145, s63, v175
	ds_read_b128 v[160:163], v145
	ds_read_b128 v[164:167], v145 offset:1024
	ds_read_b128 v[168:171], v145 offset:2048
	ds_read_b128 v[186:189], v145 offset:3072
	s_add_u32 s30, s30, s96
	s_addc_u32 s31, s31, 0
	s_mov_b32 m0, s89
	v_lshl_add_u64 v[244:245], s[30:31], 0, v[138:139]
	ds_read_b128 v[190:193], v184 offset:32768
	ds_read_b128 v[194:197], v184 offset:33792
	ds_read_b128 v[198:201], v184 offset:34816
	ds_read_b128 v[202:205], v184 offset:35840
	ds_read_b128 v[206:209], v184 offset:36864
	ds_read_b128 v[210:213], v184 offset:37888
	ds_read_b128 v[214:217], v184 offset:38912
	ds_read_b128 v[218:221], v184 offset:39936
	global_load_lds_dwordx4 v[244:245], off
	v_lshl_add_u64 v[244:245], s[30:31], 0, v[140:141]
	s_mov_b32 m0, s52
	s_nop 0
	global_load_lds_dwordx4 v[244:245], off
	s_waitcnt vmcnt(8)
	s_waitcnt lgkmcnt(0)
	s_barrier
	s_waitcnt lgkmcnt(0)
	v_mfma_f32_16x16x32_bf16 v[126:129], v[130:133], v[190:193], v[126:129]
	v_mfma_f32_16x16x32_bf16 v[122:125], v[152:155], v[190:193], v[122:125]
	v_mfma_f32_16x16x32_bf16 v[110:113], v[130:133], v[198:201], v[110:113]
	v_mfma_f32_16x16x32_bf16 v[106:109], v[152:155], v[198:201], v[106:109]
	v_mfma_f32_16x16x32_bf16 v[94:97], v[130:133], v[206:209], v[94:97]
	v_mfma_f32_16x16x32_bf16 v[90:93], v[152:155], v[206:209], v[90:93]
	v_mfma_f32_16x16x32_bf16 v[78:81], v[130:133], v[214:217], v[78:81]
	v_mfma_f32_16x16x32_bf16 v[74:77], v[152:155], v[214:217], v[74:77]
	v_mfma_f32_16x16x32_bf16 v[126:129], v[134:137], v[194:197], v[126:129]
	v_mfma_f32_16x16x32_bf16 v[122:125], v[156:159], v[194:197], v[122:125]
	v_mfma_f32_16x16x32_bf16 v[110:113], v[134:137], v[202:205], v[110:113]
	v_mfma_f32_16x16x32_bf16 v[106:109], v[156:159], v[202:205], v[106:109]
	v_mfma_f32_16x16x32_bf16 v[94:97], v[134:137], v[210:213], v[94:97]
	v_mfma_f32_16x16x32_bf16 v[90:93], v[156:159], v[210:213], v[90:93]
	v_mfma_f32_16x16x32_bf16 v[78:81], v[134:137], v[218:221], v[78:81]
	v_mfma_f32_16x16x32_bf16 v[74:77], v[156:159], v[218:221], v[74:77]
	v_mfma_f32_16x16x32_bf16 v[118:121], v[160:163], v[190:193], v[118:121]
	v_mfma_f32_16x16x32_bf16 v[114:117], v[168:171], v[190:193], v[114:117]
	v_mfma_f32_16x16x32_bf16 v[102:105], v[160:163], v[198:201], v[102:105]
	v_mfma_f32_16x16x32_bf16 v[98:101], v[168:171], v[198:201], v[98:101]
	v_mfma_f32_16x16x32_bf16 v[86:89], v[160:163], v[206:209], v[86:89]
	v_mfma_f32_16x16x32_bf16 v[82:85], v[168:171], v[206:209], v[82:85]
	v_mfma_f32_16x16x32_bf16 v[70:73], v[160:163], v[214:217], v[70:73]
	v_mfma_f32_16x16x32_bf16 v[66:69], v[168:171], v[214:217], v[66:69]
	v_mfma_f32_16x16x32_bf16 v[118:121], v[164:167], v[194:197], v[118:121]
	v_mfma_f32_16x16x32_bf16 v[114:117], v[186:189], v[194:197], v[114:117]
	v_mfma_f32_16x16x32_bf16 v[102:105], v[164:167], v[202:205], v[102:105]
	v_mfma_f32_16x16x32_bf16 v[98:101], v[186:189], v[202:205], v[98:101]
	v_mfma_f32_16x16x32_bf16 v[86:89], v[164:167], v[210:213], v[86:89]
	v_mfma_f32_16x16x32_bf16 v[82:85], v[186:189], v[210:213], v[82:85]
	v_mfma_f32_16x16x32_bf16 v[70:73], v[164:167], v[218:221], v[70:73]
	v_mfma_f32_16x16x32_bf16 v[66:69], v[186:189], v[218:221], v[66:69]
	s_barrier
	s_add_i32 s30, s62, s49
	v_lshl_add_u64 v[172:173], v[172:173], 0, s[98:99]
	s_mov_b32 m0, s30
	ds_read_b128 v[190:193], v184 offset:49152
	ds_read_b128 v[194:197], v184 offset:50176
	ds_read_b128 v[198:201], v184 offset:51200
	ds_read_b128 v[202:205], v184 offset:52224
	ds_read_b128 v[206:209], v184 offset:53248
	ds_read_b128 v[210:213], v184 offset:54272
	ds_read_b128 v[214:217], v184 offset:55296
	ds_read_b128 v[218:221], v184 offset:56320
	global_load_lds_dwordx4 v[172:173], off
	v_lshl_add_u64 v[172:173], v[222:223], 0, s[98:99]
	s_add_i32 m0, s30, 0x2000
	s_add_i32 s30, s63, s49
	global_load_lds_dwordx4 v[172:173], off
	v_lshl_add_u64 v[172:173], v[236:237], 0, s[98:99]
	s_mov_b32 m0, s30
	s_nop 0
	global_load_lds_dwordx4 v[172:173], off
	v_lshl_add_u64 v[172:173], v[238:239], 0, s[98:99]
	s_add_i32 m0, s30, 0x2000
	s_nop 0
	global_load_lds_dwordx4 v[172:173], off
	v_lshl_add_u64 v[172:173], v[240:241], 0, s[98:99]
	s_mov_b32 m0, s95
	s_nop 0
	global_load_lds_dwordx4 v[172:173], off
	v_lshl_add_u64 v[172:173], v[242:243], 0, s[98:99]
	s_mov_b32 m0, s54
	s_nop 0
	global_load_lds_dwordx4 v[172:173], off
	s_waitcnt vmcnt(8)
	s_waitcnt lgkmcnt(0)
	s_barrier
	s_waitcnt lgkmcnt(0)
	v_mfma_f32_16x16x32_bf16 v[62:65], v[130:133], v[190:193], v[62:65]
	v_mfma_f32_16x16x32_bf16 v[58:61], v[152:155], v[190:193], v[58:61]
	v_mfma_f32_16x16x32_bf16 v[46:49], v[130:133], v[198:201], v[46:49]
	v_mfma_f32_16x16x32_bf16 v[42:45], v[152:155], v[198:201], v[42:45]
	v_mfma_f32_16x16x32_bf16 v[30:33], v[130:133], v[206:209], v[30:33]
	v_mfma_f32_16x16x32_bf16 v[26:29], v[152:155], v[206:209], v[26:29]
	v_mfma_f32_16x16x32_bf16 v[14:17], v[130:133], v[214:217], v[14:17]
	v_mfma_f32_16x16x32_bf16 v[10:13], v[152:155], v[214:217], v[10:13]
	v_mfma_f32_16x16x32_bf16 v[62:65], v[134:137], v[194:197], v[62:65]
	v_mfma_f32_16x16x32_bf16 v[58:61], v[156:159], v[194:197], v[58:61]
	v_mfma_f32_16x16x32_bf16 v[46:49], v[134:137], v[202:205], v[46:49]
	v_mfma_f32_16x16x32_bf16 v[42:45], v[156:159], v[202:205], v[42:45]
	v_mfma_f32_16x16x32_bf16 v[30:33], v[134:137], v[210:213], v[30:33]
	v_mfma_f32_16x16x32_bf16 v[26:29], v[156:159], v[210:213], v[26:29]
	v_mfma_f32_16x16x32_bf16 v[14:17], v[134:137], v[218:221], v[14:17]
	v_mfma_f32_16x16x32_bf16 v[10:13], v[156:159], v[218:221], v[10:13]
	v_mfma_f32_16x16x32_bf16 v[54:57], v[160:163], v[190:193], v[54:57]
	v_mfma_f32_16x16x32_bf16 v[50:53], v[168:171], v[190:193], v[50:53]
	v_mfma_f32_16x16x32_bf16 v[38:41], v[160:163], v[198:201], v[38:41]
	v_mfma_f32_16x16x32_bf16 v[34:37], v[168:171], v[198:201], v[34:37]
	v_mfma_f32_16x16x32_bf16 v[22:25], v[160:163], v[206:209], v[22:25]
	v_mfma_f32_16x16x32_bf16 v[18:21], v[168:171], v[206:209], v[18:21]
	v_mfma_f32_16x16x32_bf16 v[6:9], v[160:163], v[214:217], v[6:9]
	v_mfma_f32_16x16x32_bf16 v[2:5], v[168:171], v[214:217], v[2:5]
	v_mfma_f32_16x16x32_bf16 v[54:57], v[164:167], v[194:197], v[54:57]
	v_mfma_f32_16x16x32_bf16 v[50:53], v[186:189], v[194:197], v[50:53]
	v_mfma_f32_16x16x32_bf16 v[38:41], v[164:167], v[202:205], v[38:41]
	v_mfma_f32_16x16x32_bf16 v[34:37], v[186:189], v[202:205], v[34:37]
	v_mfma_f32_16x16x32_bf16 v[22:25], v[164:167], v[210:213], v[22:25]
	v_mfma_f32_16x16x32_bf16 v[18:21], v[186:189], v[210:213], v[18:21]
	v_mfma_f32_16x16x32_bf16 v[6:9], v[164:167], v[218:221], v[6:9]
	v_mfma_f32_16x16x32_bf16 v[2:5], v[186:189], v[218:221], v[2:5]
	s_barrier
	s_add_u32 s28, s28, 0x100
	s_addc_u32 s29, s29, 0
	s_add_u32 s23, s23, 0x100
	s_addc_u32 s40, s40, 0
	s_cmp_ge_i32 s41, s61
	s_mov_b32 s30, s41
	s_cbranch_scc1 .Lpeel_done_217
.LBB0_217:
	s_add_i32 s41, s30, 2
	s_add_u32 vcc_lo, s28, 0x80
	s_addc_u32 s31, s29, 0
	s_add_i32 s62, 0, 0x10000
	s_cmp_eq_u32 s13, s30
	s_cselect_b32 s31, s25, s31
	s_cselect_b32 s30, s24, vcc_lo
	v_add_u32_e32 v145, s62, v175
	s_cselect_b32 vcc_hi, s27, s40
	s_cselect_b32 vcc_lo, s26, s23
	s_add_i32 s63, 0, 0x14000
	ds_read_b128 v[130:133], v145
	ds_read_b128 v[134:137], v145 offset:1024
	ds_read_b128 v[152:155], v145 offset:2048
	ds_read_b128 v[156:159], v145 offset:3072
	v_add_u32_e32 v145, s63, v175
	ds_read_b128 v[160:163], v145
	ds_read_b128 v[164:167], v145 offset:1024
	ds_read_b128 v[168:171], v145 offset:2048
	ds_read_b128 v[186:189], v145 offset:3072
	v_lshl_add_u64 v[172:173], s[28:29], 0, v[148:149]
	s_add_i32 m0, s93, 0xc000
	ds_read_b128 v[190:193], v184
	ds_read_b128 v[194:197], v184 offset:1024
	ds_read_b128 v[198:201], v184 offset:2048
	ds_read_b128 v[202:205], v184 offset:3072
	ds_read_b128 v[206:209], v184 offset:4096
	ds_read_b128 v[210:213], v184 offset:5120
	ds_read_b128 v[214:217], v184 offset:6144
	ds_read_b128 v[218:221], v184 offset:7168
	global_load_lds_dwordx4 v[172:173], off
	v_lshl_add_u64 v[172:173], s[28:29], 0, v[150:151]
	s_add_i32 m0, s93, 0xe000
	s_nop 0
	global_load_lds_dwordx4 v[172:173], off
	s_waitcnt vmcnt(8)
	s_waitcnt lgkmcnt(0)
	s_barrier
	s_waitcnt lgkmcnt(0)
	v_mfma_f32_16x16x32_bf16 v[126:129], v[130:133], v[190:193], v[126:129]
	v_mfma_f32_16x16x32_bf16 v[122:125], v[152:155], v[190:193], v[122:125]
	v_mfma_f32_16x16x32_bf16 v[110:113], v[130:133], v[198:201], v[110:113]
	v_mfma_f32_16x16x32_bf16 v[106:109], v[152:155], v[198:201], v[106:109]
	v_mfma_f32_16x16x32_bf16 v[94:97], v[130:133], v[206:209], v[94:97]
	v_mfma_f32_16x16x32_bf16 v[90:93], v[152:155], v[206:209], v[90:93]
	v_mfma_f32_16x16x32_bf16 v[78:81], v[130:133], v[214:217], v[78:81]
	v_mfma_f32_16x16x32_bf16 v[74:77], v[152:155], v[214:217], v[74:77]
	v_mfma_f32_16x16x32_bf16 v[126:129], v[134:137], v[194:197], v[126:129]
	v_mfma_f32_16x16x32_bf16 v[122:125], v[156:159], v[194:197], v[122:125]
	v_mfma_f32_16x16x32_bf16 v[110:113], v[134:137], v[202:205], v[110:113]
	v_mfma_f32_16x16x32_bf16 v[106:109], v[156:159], v[202:205], v[106:109]
	v_mfma_f32_16x16x32_bf16 v[94:97], v[134:137], v[210:213], v[94:97]
	v_mfma_f32_16x16x32_bf16 v[90:93], v[156:159], v[210:213], v[90:93]
	v_mfma_f32_16x16x32_bf16 v[78:81], v[134:137], v[218:221], v[78:81]
	v_mfma_f32_16x16x32_bf16 v[74:77], v[156:159], v[218:221], v[74:77]
	v_mfma_f32_16x16x32_bf16 v[118:121], v[160:163], v[190:193], v[118:121]
	v_mfma_f32_16x16x32_bf16 v[114:117], v[168:171], v[190:193], v[114:117]
	v_mfma_f32_16x16x32_bf16 v[102:105], v[160:163], v[198:201], v[102:105]
	v_mfma_f32_16x16x32_bf16 v[98:101], v[168:171], v[198:201], v[98:101]
	v_mfma_f32_16x16x32_bf16 v[86:89], v[160:163], v[206:209], v[86:89]
	v_mfma_f32_16x16x32_bf16 v[82:85], v[168:171], v[206:209], v[82:85]
	v_mfma_f32_16x16x32_bf16 v[70:73], v[160:163], v[214:217], v[70:73]
	v_mfma_f32_16x16x32_bf16 v[66:69], v[168:171], v[214:217], v[66:69]
	v_mfma_f32_16x16x32_bf16 v[118:121], v[164:167], v[194:197], v[118:121]
	v_mfma_f32_16x16x32_bf16 v[114:117], v[186:189], v[194:197], v[114:117]
	v_mfma_f32_16x16x32_bf16 v[102:105], v[164:167], v[202:205], v[102:105]
	v_mfma_f32_16x16x32_bf16 v[98:101], v[186:189], v[202:205], v[98:101]
	v_mfma_f32_16x16x32_bf16 v[86:89], v[164:167], v[210:213], v[86:89]
	v_mfma_f32_16x16x32_bf16 v[82:85], v[186:189], v[210:213], v[82:85]
	v_mfma_f32_16x16x32_bf16 v[70:73], v[164:167], v[218:221], v[70:73]
	v_mfma_f32_16x16x32_bf16 v[66:69], v[186:189], v[218:221], v[66:69]
	s_barrier
	s_add_i32 s62, s62, s49
	v_lshl_add_u64 v[172:173], vcc, 0, v[0:1]
	s_mov_b32 m0, s62
	ds_read_b128 v[190:193], v184 offset:16384
	ds_read_b128 v[194:197], v184 offset:17408
	ds_read_b128 v[198:201], v184 offset:18432
	ds_read_b128 v[202:205], v184 offset:19456
	ds_read_b128 v[206:209], v184 offset:20480
	ds_read_b128 v[210:213], v184 offset:21504
	ds_read_b128 v[214:217], v184 offset:22528
	ds_read_b128 v[218:221], v184 offset:23552
	global_load_lds_dwordx4 v[172:173], off
	s_add_i32 m0, s62, 0x2000
	v_lshl_add_u64 v[222:223], vcc, 0, v[142:143]
	s_add_u32 vcc_lo, vcc_lo, s96
	s_addc_u32 vcc_hi, vcc_hi, 0
	s_add_i32 s62, s63, s49
	global_load_lds_dwordx4 v[222:223], off
	v_lshl_add_u64 v[236:237], vcc, 0, v[0:1]
	s_mov_b32 m0, s62
	v_lshl_add_u64 v[238:239], vcc, 0, v[142:143]
	global_load_lds_dwordx4 v[236:237], off
	s_add_i32 m0, s62, 0x2000
	v_lshl_add_u64 v[240:241], s[30:31], 0, v[138:139]
	global_load_lds_dwordx4 v[238:239], off
	s_mov_b32 m0, s93
	v_lshl_add_u64 v[242:243], s[30:31], 0, v[140:141]
	global_load_lds_dwordx4 v[240:241], off
	s_mov_b32 m0, s88
	s_nop 0
	global_load_lds_dwordx4 v[242:243], off
	s_waitcnt vmcnt(8)
	s_waitcnt lgkmcnt(0)
	s_barrier
	s_waitcnt lgkmcnt(0)
	v_mfma_f32_16x16x32_bf16 v[62:65], v[130:133], v[190:193], v[62:65]
	v_mfma_f32_16x16x32_bf16 v[58:61], v[152:155], v[190:193], v[58:61]
	v_mfma_f32_16x16x32_bf16 v[46:49], v[130:133], v[198:201], v[46:49]
	v_mfma_f32_16x16x32_bf16 v[42:45], v[152:155], v[198:201], v[42:45]
	v_mfma_f32_16x16x32_bf16 v[30:33], v[130:133], v[206:209], v[30:33]
	v_mfma_f32_16x16x32_bf16 v[26:29], v[152:155], v[206:209], v[26:29]
	v_mfma_f32_16x16x32_bf16 v[14:17], v[130:133], v[214:217], v[14:17]
	v_mfma_f32_16x16x32_bf16 v[10:13], v[152:155], v[214:217], v[10:13]
	v_mfma_f32_16x16x32_bf16 v[62:65], v[134:137], v[194:197], v[62:65]
	v_mfma_f32_16x16x32_bf16 v[58:61], v[156:159], v[194:197], v[58:61]
	v_mfma_f32_16x16x32_bf16 v[46:49], v[134:137], v[202:205], v[46:49]
	v_mfma_f32_16x16x32_bf16 v[42:45], v[156:159], v[202:205], v[42:45]
	v_mfma_f32_16x16x32_bf16 v[30:33], v[134:137], v[210:213], v[30:33]
	v_mfma_f32_16x16x32_bf16 v[26:29], v[156:159], v[210:213], v[26:29]
	v_mfma_f32_16x16x32_bf16 v[14:17], v[134:137], v[218:221], v[14:17]
	v_mfma_f32_16x16x32_bf16 v[10:13], v[156:159], v[218:221], v[10:13]
	v_mfma_f32_16x16x32_bf16 v[54:57], v[160:163], v[190:193], v[54:57]
	v_mfma_f32_16x16x32_bf16 v[50:53], v[168:171], v[190:193], v[50:53]
	v_mfma_f32_16x16x32_bf16 v[38:41], v[160:163], v[198:201], v[38:41]
	v_mfma_f32_16x16x32_bf16 v[34:37], v[168:171], v[198:201], v[34:37]
	v_mfma_f32_16x16x32_bf16 v[22:25], v[160:163], v[206:209], v[22:25]
	v_mfma_f32_16x16x32_bf16 v[18:21], v[168:171], v[206:209], v[18:21]
	v_mfma_f32_16x16x32_bf16 v[6:9], v[160:163], v[214:217], v[6:9]
	v_mfma_f32_16x16x32_bf16 v[2:5], v[168:171], v[214:217], v[2:5]
	v_mfma_f32_16x16x32_bf16 v[54:57], v[164:167], v[194:197], v[54:57]
	v_mfma_f32_16x16x32_bf16 v[50:53], v[186:189], v[194:197], v[50:53]
	v_mfma_f32_16x16x32_bf16 v[38:41], v[164:167], v[202:205], v[38:41]
	v_mfma_f32_16x16x32_bf16 v[34:37], v[186:189], v[202:205], v[34:37]
	v_mfma_f32_16x16x32_bf16 v[22:25], v[164:167], v[210:213], v[22:25]
	v_mfma_f32_16x16x32_bf16 v[18:21], v[186:189], v[210:213], v[18:21]
	v_mfma_f32_16x16x32_bf16 v[6:9], v[164:167], v[218:221], v[6:9]
	v_mfma_f32_16x16x32_bf16 v[2:5], v[186:189], v[218:221], v[2:5]
	s_barrier
	s_add_i32 s62, 0, 0x18000
	v_add_u32_e32 v145, s62, v175
	s_add_i32 s63, 0, 0x1c000
	ds_read_b128 v[130:133], v145
	ds_read_b128 v[134:137], v145 offset:1024
	ds_read_b128 v[152:155], v145 offset:2048
	ds_read_b128 v[156:159], v145 offset:3072
	v_add_u32_e32 v145, s63, v175
	ds_read_b128 v[160:163], v145
	ds_read_b128 v[164:167], v145 offset:1024
	ds_read_b128 v[168:171], v145 offset:2048
	ds_read_b128 v[186:189], v145 offset:3072
	s_add_u32 s30, s30, s96
	s_addc_u32 s31, s31, 0
	s_mov_b32 m0, s89
	v_lshl_add_u64 v[244:245], s[30:31], 0, v[138:139]
	ds_read_b128 v[190:193], v184 offset:32768
	ds_read_b128 v[194:197], v184 offset:33792
	ds_read_b128 v[198:201], v184 offset:34816
	ds_read_b128 v[202:205], v184 offset:35840
	ds_read_b128 v[206:209], v184 offset:36864
	ds_read_b128 v[210:213], v184 offset:37888
	ds_read_b128 v[214:217], v184 offset:38912
	ds_read_b128 v[218:221], v184 offset:39936
	global_load_lds_dwordx4 v[244:245], off
	v_lshl_add_u64 v[244:245], s[30:31], 0, v[140:141]
	s_mov_b32 m0, s52
	s_nop 0
	global_load_lds_dwordx4 v[244:245], off
	s_waitcnt vmcnt(8)
	s_waitcnt lgkmcnt(0)
	s_barrier
	s_waitcnt lgkmcnt(0)
	v_mfma_f32_16x16x32_bf16 v[126:129], v[130:133], v[190:193], v[126:129]
	v_mfma_f32_16x16x32_bf16 v[122:125], v[152:155], v[190:193], v[122:125]
	v_mfma_f32_16x16x32_bf16 v[110:113], v[130:133], v[198:201], v[110:113]
	v_mfma_f32_16x16x32_bf16 v[106:109], v[152:155], v[198:201], v[106:109]
	v_mfma_f32_16x16x32_bf16 v[94:97], v[130:133], v[206:209], v[94:97]
	v_mfma_f32_16x16x32_bf16 v[90:93], v[152:155], v[206:209], v[90:93]
	v_mfma_f32_16x16x32_bf16 v[78:81], v[130:133], v[214:217], v[78:81]
	v_mfma_f32_16x16x32_bf16 v[74:77], v[152:155], v[214:217], v[74:77]
	v_mfma_f32_16x16x32_bf16 v[126:129], v[134:137], v[194:197], v[126:129]
	v_mfma_f32_16x16x32_bf16 v[122:125], v[156:159], v[194:197], v[122:125]
	v_mfma_f32_16x16x32_bf16 v[110:113], v[134:137], v[202:205], v[110:113]
	v_mfma_f32_16x16x32_bf16 v[106:109], v[156:159], v[202:205], v[106:109]
	v_mfma_f32_16x16x32_bf16 v[94:97], v[134:137], v[210:213], v[94:97]
	v_mfma_f32_16x16x32_bf16 v[90:93], v[156:159], v[210:213], v[90:93]
	v_mfma_f32_16x16x32_bf16 v[78:81], v[134:137], v[218:221], v[78:81]
	v_mfma_f32_16x16x32_bf16 v[74:77], v[156:159], v[218:221], v[74:77]
	v_mfma_f32_16x16x32_bf16 v[118:121], v[160:163], v[190:193], v[118:121]
	v_mfma_f32_16x16x32_bf16 v[114:117], v[168:171], v[190:193], v[114:117]
	v_mfma_f32_16x16x32_bf16 v[102:105], v[160:163], v[198:201], v[102:105]
	v_mfma_f32_16x16x32_bf16 v[98:101], v[168:171], v[198:201], v[98:101]
	v_mfma_f32_16x16x32_bf16 v[86:89], v[160:163], v[206:209], v[86:89]
	v_mfma_f32_16x16x32_bf16 v[82:85], v[168:171], v[206:209], v[82:85]
	v_mfma_f32_16x16x32_bf16 v[70:73], v[160:163], v[214:217], v[70:73]
	v_mfma_f32_16x16x32_bf16 v[66:69], v[168:171], v[214:217], v[66:69]
	v_mfma_f32_16x16x32_bf16 v[118:121], v[164:167], v[194:197], v[118:121]
	v_mfma_f32_16x16x32_bf16 v[114:117], v[186:189], v[194:197], v[114:117]
	v_mfma_f32_16x16x32_bf16 v[102:105], v[164:167], v[202:205], v[102:105]
	v_mfma_f32_16x16x32_bf16 v[98:101], v[186:189], v[202:205], v[98:101]
	v_mfma_f32_16x16x32_bf16 v[86:89], v[164:167], v[210:213], v[86:89]
	v_mfma_f32_16x16x32_bf16 v[82:85], v[186:189], v[210:213], v[82:85]
	v_mfma_f32_16x16x32_bf16 v[70:73], v[164:167], v[218:221], v[70:73]
	v_mfma_f32_16x16x32_bf16 v[66:69], v[186:189], v[218:221], v[66:69]
	s_barrier
	s_add_i32 s30, s62, s49
	v_lshl_add_u64 v[172:173], v[172:173], 0, s[98:99]
	s_mov_b32 m0, s30
	ds_read_b128 v[190:193], v184 offset:49152
	ds_read_b128 v[194:197], v184 offset:50176
	ds_read_b128 v[198:201], v184 offset:51200
	ds_read_b128 v[202:205], v184 offset:52224
	ds_read_b128 v[206:209], v184 offset:53248
	ds_read_b128 v[210:213], v184 offset:54272
	ds_read_b128 v[214:217], v184 offset:55296
	ds_read_b128 v[218:221], v184 offset:56320
	global_load_lds_dwordx4 v[172:173], off
	v_lshl_add_u64 v[172:173], v[222:223], 0, s[98:99]
	s_add_i32 m0, s30, 0x2000
	s_add_i32 s30, s63, s49
	global_load_lds_dwordx4 v[172:173], off
	v_lshl_add_u64 v[172:173], v[236:237], 0, s[98:99]
	s_mov_b32 m0, s30
	s_nop 0
	global_load_lds_dwordx4 v[172:173], off
	v_lshl_add_u64 v[172:173], v[238:239], 0, s[98:99]
	s_add_i32 m0, s30, 0x2000
	s_nop 0
	global_load_lds_dwordx4 v[172:173], off
	v_lshl_add_u64 v[172:173], v[240:241], 0, s[98:99]
	s_mov_b32 m0, s95
	s_nop 0
	global_load_lds_dwordx4 v[172:173], off
	v_lshl_add_u64 v[172:173], v[242:243], 0, s[98:99]
	s_mov_b32 m0, s54
	s_nop 0
	global_load_lds_dwordx4 v[172:173], off
	s_waitcnt vmcnt(8)
	s_waitcnt lgkmcnt(0)
	s_barrier
	s_waitcnt lgkmcnt(0)
	v_mfma_f32_16x16x32_bf16 v[62:65], v[130:133], v[190:193], v[62:65]
	v_mfma_f32_16x16x32_bf16 v[58:61], v[152:155], v[190:193], v[58:61]
	v_mfma_f32_16x16x32_bf16 v[46:49], v[130:133], v[198:201], v[46:49]
	v_mfma_f32_16x16x32_bf16 v[42:45], v[152:155], v[198:201], v[42:45]
	v_mfma_f32_16x16x32_bf16 v[30:33], v[130:133], v[206:209], v[30:33]
	v_mfma_f32_16x16x32_bf16 v[26:29], v[152:155], v[206:209], v[26:29]
	v_mfma_f32_16x16x32_bf16 v[14:17], v[130:133], v[214:217], v[14:17]
	v_mfma_f32_16x16x32_bf16 v[10:13], v[152:155], v[214:217], v[10:13]
	v_mfma_f32_16x16x32_bf16 v[62:65], v[134:137], v[194:197], v[62:65]
	v_mfma_f32_16x16x32_bf16 v[58:61], v[156:159], v[194:197], v[58:61]
	v_mfma_f32_16x16x32_bf16 v[46:49], v[134:137], v[202:205], v[46:49]
	v_mfma_f32_16x16x32_bf16 v[42:45], v[156:159], v[202:205], v[42:45]
	v_mfma_f32_16x16x32_bf16 v[30:33], v[134:137], v[210:213], v[30:33]
	v_mfma_f32_16x16x32_bf16 v[26:29], v[156:159], v[210:213], v[26:29]
	v_mfma_f32_16x16x32_bf16 v[14:17], v[134:137], v[218:221], v[14:17]
	v_mfma_f32_16x16x32_bf16 v[10:13], v[156:159], v[218:221], v[10:13]
	v_mfma_f32_16x16x32_bf16 v[54:57], v[160:163], v[190:193], v[54:57]
	v_mfma_f32_16x16x32_bf16 v[50:53], v[168:171], v[190:193], v[50:53]
	v_mfma_f32_16x16x32_bf16 v[38:41], v[160:163], v[198:201], v[38:41]
	v_mfma_f32_16x16x32_bf16 v[34:37], v[168:171], v[198:201], v[34:37]
	v_mfma_f32_16x16x32_bf16 v[22:25], v[160:163], v[206:209], v[22:25]
	v_mfma_f32_16x16x32_bf16 v[18:21], v[168:171], v[206:209], v[18:21]
	v_mfma_f32_16x16x32_bf16 v[6:9], v[160:163], v[214:217], v[6:9]
	v_mfma_f32_16x16x32_bf16 v[2:5], v[168:171], v[214:217], v[2:5]
	v_mfma_f32_16x16x32_bf16 v[54:57], v[164:167], v[194:197], v[54:57]
	v_mfma_f32_16x16x32_bf16 v[50:53], v[186:189], v[194:197], v[50:53]
	v_mfma_f32_16x16x32_bf16 v[38:41], v[164:167], v[202:205], v[38:41]
	v_mfma_f32_16x16x32_bf16 v[34:37], v[186:189], v[202:205], v[34:37]
	v_mfma_f32_16x16x32_bf16 v[22:25], v[164:167], v[210:213], v[22:25]
	v_mfma_f32_16x16x32_bf16 v[18:21], v[186:189], v[210:213], v[18:21]
	v_mfma_f32_16x16x32_bf16 v[6:9], v[164:167], v[218:221], v[6:9]
	v_mfma_f32_16x16x32_bf16 v[2:5], v[186:189], v[218:221], v[2:5]
	s_barrier
	s_add_u32 s28, s28, 0x100
	s_addc_u32 s29, s29, 0
	s_add_u32 s23, s23, 0x100
	s_addc_u32 s40, s40, 0
	s_cmp_ge_i32 s41, s61
	s_mov_b32 s30, s41
	s_cbranch_scc0 .LBB0_217

.LBB0_373:
	s_ashr_i32 s17, s16, 31
	s_lshl_b64 s[20:21], s[16:17], 19
	s_add_u32 s20, s37, s20
	s_addc_u32 s21, s40, s21
	s_and_b64 s[22:23], s[18:19], exec
	s_cselect_b32 s17, s21, s29
	s_cselect_b32 s25, s20, s28
	s_ashr_i32 s15, s14, 31
	s_lshl_b64 s[22:23], s[14:15], 19
	s_add_u32 s22, s41, s22
	s_addc_u32 s23, s42, s23
	s_and_b64 s[38:39], s[18:19], exec
	s_cselect_b32 s15, s23, s31
	s_cselect_b32 s53, s22, s30
	s_add_u32 s28, s28, 0x40080
	s_addc_u32 s29, s29, 0
	s_add_u32 s54, s30, 0x100
	s_addc_u32 s55, s31, 0
	s_mov_b32 s56, -2
	s_add_u32 s30, s28, 0xfffc0080
	s_addc_u32 s31, s29, -1
	s_add_i32 s57, 0, 0x10000
	s_cmp_eq_u32 s56, 12
	s_cselect_b32 s39, s17, s31
	s_cselect_b32 s38, s25, s30
	s_cselect_b32 s31, s15, s55
	s_cselect_b32 s30, s53, s54
	s_add_i32 s60, 0, 0x14000
	v_add_u32_e32 v156, s57, v145
	v_add_u32_e32 v172, s60, v145
	ds_read_b128 v[140:143], v156
	ds_read_b128 v[148:151], v156 offset:1024
	ds_read_b128 v[152:155], v156 offset:2048
	ds_read_b128 v[156:159], v156 offset:3072
	ds_read_b128 v[160:163], v172
	ds_read_b128 v[164:167], v172 offset:1024
	ds_read_b128 v[168:171], v172 offset:2048
	ds_read_b128 v[172:175], v172 offset:3072
	v_lshl_add_u64 v[208:209], s[28:29], 0, v[136:137]
	s_add_i32 m0, s27, 0xc000
	ds_read_b128 v[176:179], v147
	ds_read_b128 v[180:183], v147 offset:1024
	ds_read_b128 v[184:187], v147 offset:2048
	ds_read_b128 v[188:191], v147 offset:3072
	ds_read_b128 v[192:195], v147 offset:4096
	ds_read_b128 v[196:199], v147 offset:5120
	ds_read_b128 v[200:203], v147 offset:6144
	ds_read_b128 v[204:207], v147 offset:7168
	global_load_lds_dwordx4 v[208:209], off
	v_lshl_add_u64 v[208:209], s[28:29], 0, v[138:139]
	s_add_i32 m0, s27, 0xe000
	s_nop 0
	global_load_lds_dwordx4 v[208:209], off
	s_waitcnt vmcnt(8)
	s_waitcnt lgkmcnt(0)
	s_barrier
	s_waitcnt lgkmcnt(0)
	v_mfma_f32_16x16x32_bf16 v[122:125], v[140:143], v[176:179], 0
	v_mfma_f32_16x16x32_bf16 v[114:117], v[152:155], v[176:179], 0
	v_mfma_f32_16x16x32_bf16 v[106:109], v[140:143], v[184:187], 0
	v_mfma_f32_16x16x32_bf16 v[98:101], v[152:155], v[184:187], 0
	v_mfma_f32_16x16x32_bf16 v[90:93], v[140:143], v[192:195], 0
	v_mfma_f32_16x16x32_bf16 v[82:85], v[152:155], v[192:195], 0
	v_mfma_f32_16x16x32_bf16 v[74:77], v[140:143], v[200:203], 0
	v_mfma_f32_16x16x32_bf16 v[66:69], v[152:155], v[200:203], 0
	v_mfma_f32_16x16x32_bf16 v[122:125], v[148:151], v[180:183], v[122:125]
	v_mfma_f32_16x16x32_bf16 v[114:117], v[156:159], v[180:183], v[114:117]
	v_mfma_f32_16x16x32_bf16 v[106:109], v[148:151], v[188:191], v[106:109]
	v_mfma_f32_16x16x32_bf16 v[98:101], v[156:159], v[188:191], v[98:101]
	v_mfma_f32_16x16x32_bf16 v[90:93], v[148:151], v[196:199], v[90:93]
	v_mfma_f32_16x16x32_bf16 v[82:85], v[156:159], v[196:199], v[82:85]
	v_mfma_f32_16x16x32_bf16 v[74:77], v[148:151], v[204:207], v[74:77]
	v_mfma_f32_16x16x32_bf16 v[66:69], v[156:159], v[204:207], v[66:69]
	v_mfma_f32_16x16x32_bf16 v[126:129], v[160:163], v[176:179], 0
	v_mfma_f32_16x16x32_bf16 v[118:121], v[168:171], v[176:179], 0
	v_mfma_f32_16x16x32_bf16 v[110:113], v[160:163], v[184:187], 0
	v_mfma_f32_16x16x32_bf16 v[102:105], v[168:171], v[184:187], 0
	v_mfma_f32_16x16x32_bf16 v[94:97], v[160:163], v[192:195], 0
	v_mfma_f32_16x16x32_bf16 v[86:89], v[168:171], v[192:195], 0
	v_mfma_f32_16x16x32_bf16 v[78:81], v[160:163], v[200:203], 0
	v_mfma_f32_16x16x32_bf16 v[70:73], v[168:171], v[200:203], 0
	v_mfma_f32_16x16x32_bf16 v[126:129], v[164:167], v[180:183], v[126:129]
	v_mfma_f32_16x16x32_bf16 v[118:121], v[172:175], v[180:183], v[118:121]
	v_mfma_f32_16x16x32_bf16 v[110:113], v[164:167], v[188:191], v[110:113]
	v_mfma_f32_16x16x32_bf16 v[102:105], v[172:175], v[188:191], v[102:105]
	v_mfma_f32_16x16x32_bf16 v[94:97], v[164:167], v[196:199], v[94:97]
	v_mfma_f32_16x16x32_bf16 v[86:89], v[172:175], v[196:199], v[86:89]
	v_mfma_f32_16x16x32_bf16 v[78:81], v[164:167], v[204:207], v[78:81]
	v_mfma_f32_16x16x32_bf16 v[70:73], v[172:175], v[204:207], v[70:73]
	s_barrier
	s_add_i32 s57, s57, s43
	v_lshl_add_u64 v[208:209], s[30:31], 0, v[0:1]
	s_mov_b32 m0, s57
	ds_read_b128 v[176:179], v147 offset:16384
	ds_read_b128 v[180:183], v147 offset:17408
	ds_read_b128 v[184:187], v147 offset:18432
	ds_read_b128 v[188:191], v147 offset:19456
	ds_read_b128 v[192:195], v147 offset:20480
	ds_read_b128 v[196:199], v147 offset:21504
	ds_read_b128 v[200:203], v147 offset:22528
	ds_read_b128 v[204:207], v147 offset:23552
	global_load_lds_dwordx4 v[208:209], off
	s_add_i32 m0, s57, 0x2000
	s_add_u32 s58, s30, 0x40000
	v_lshl_add_u64 v[210:211], s[30:31], 0, v[134:135]
	s_addc_u32 s59, s31, 0
	s_add_i32 s57, s60, s43
	global_load_lds_dwordx4 v[210:211], off
	v_lshl_add_u64 v[212:213], s[58:59], 0, v[0:1]
	s_mov_b32 m0, s57
	v_lshl_add_u64 v[214:215], s[38:39], 0, v[132:133]
	global_load_lds_dwordx4 v[212:213], off
	v_lshl_add_u64 v[212:213], s[58:59], 0, v[134:135]
	s_add_i32 m0, s57, 0x2000
	s_nop 0
	global_load_lds_dwordx4 v[212:213], off
	v_lshl_add_u64 v[212:213], s[38:39], 0, v[130:131]
	s_mov_b32 m0, s27
	s_nop 0
	global_load_lds_dwordx4 v[212:213], off
	s_mov_b32 m0, s44
	s_nop 0
	global_load_lds_dwordx4 v[214:215], off
	s_waitcnt vmcnt(8)
	s_waitcnt lgkmcnt(0)
	s_barrier
	s_waitcnt lgkmcnt(0)
	v_mfma_f32_16x16x32_bf16 v[58:61], v[140:143], v[176:179], 0
	v_mfma_f32_16x16x32_bf16 v[50:53], v[152:155], v[176:179], 0
	v_mfma_f32_16x16x32_bf16 v[42:45], v[140:143], v[184:187], 0
	v_mfma_f32_16x16x32_bf16 v[34:37], v[152:155], v[184:187], 0
	v_mfma_f32_16x16x32_bf16 v[26:29], v[140:143], v[192:195], 0
	v_mfma_f32_16x16x32_bf16 v[18:21], v[152:155], v[192:195], 0
	v_mfma_f32_16x16x32_bf16 v[10:13], v[140:143], v[200:203], 0
	v_mfma_f32_16x16x32_bf16 v[6:9], v[152:155], v[200:203], 0
	v_mfma_f32_16x16x32_bf16 v[58:61], v[148:151], v[180:183], v[58:61]
	v_mfma_f32_16x16x32_bf16 v[50:53], v[156:159], v[180:183], v[50:53]
	v_mfma_f32_16x16x32_bf16 v[42:45], v[148:151], v[188:191], v[42:45]
	v_mfma_f32_16x16x32_bf16 v[34:37], v[156:159], v[188:191], v[34:37]
	v_mfma_f32_16x16x32_bf16 v[26:29], v[148:151], v[196:199], v[26:29]
	v_mfma_f32_16x16x32_bf16 v[18:21], v[156:159], v[196:199], v[18:21]
	v_mfma_f32_16x16x32_bf16 v[10:13], v[148:151], v[204:207], v[10:13]
	v_mfma_f32_16x16x32_bf16 v[6:9], v[156:159], v[204:207], v[6:9]
	v_mfma_f32_16x16x32_bf16 v[62:65], v[160:163], v[176:179], 0
	v_mfma_f32_16x16x32_bf16 v[54:57], v[168:171], v[176:179], 0
	v_mfma_f32_16x16x32_bf16 v[46:49], v[160:163], v[184:187], 0
	v_mfma_f32_16x16x32_bf16 v[38:41], v[168:171], v[184:187], 0
	v_mfma_f32_16x16x32_bf16 v[30:33], v[160:163], v[192:195], 0
	v_mfma_f32_16x16x32_bf16 v[22:25], v[168:171], v[192:195], 0
	v_mfma_f32_16x16x32_bf16 v[14:17], v[160:163], v[200:203], 0
	v_mfma_f32_16x16x32_bf16 v[2:5], v[168:171], v[200:203], 0
	v_mfma_f32_16x16x32_bf16 v[62:65], v[164:167], v[180:183], v[62:65]
	v_mfma_f32_16x16x32_bf16 v[54:57], v[172:175], v[180:183], v[54:57]
	v_mfma_f32_16x16x32_bf16 v[46:49], v[164:167], v[188:191], v[46:49]
	v_mfma_f32_16x16x32_bf16 v[38:41], v[172:175], v[188:191], v[38:41]
	v_mfma_f32_16x16x32_bf16 v[30:33], v[164:167], v[196:199], v[30:33]
	v_mfma_f32_16x16x32_bf16 v[22:25], v[172:175], v[196:199], v[22:25]
	v_mfma_f32_16x16x32_bf16 v[14:17], v[164:167], v[204:207], v[14:17]
	v_mfma_f32_16x16x32_bf16 v[2:5], v[172:175], v[204:207], v[2:5]
	s_barrier
	s_add_i32 s57, 0, 0x18000
	s_add_i32 s58, 0, 0x1c000
	v_add_u32_e32 v156, s57, v145
	v_add_u32_e32 v172, s58, v145
	ds_read_b128 v[140:143], v156
	ds_read_b128 v[148:151], v156 offset:1024
	ds_read_b128 v[152:155], v156 offset:2048
	ds_read_b128 v[156:159], v156 offset:3072
	ds_read_b128 v[160:163], v172
	ds_read_b128 v[164:167], v172 offset:1024
	ds_read_b128 v[168:171], v172 offset:2048
	ds_read_b128 v[172:175], v172 offset:3072
	s_add_u32 s38, s38, 0x40000
	s_addc_u32 s39, s39, 0
	s_mov_b32 m0, s45
	v_lshl_add_u64 v[216:217], s[38:39], 0, v[130:131]
	ds_read_b128 v[176:179], v147 offset:32768
	ds_read_b128 v[180:183], v147 offset:33792
	ds_read_b128 v[184:187], v147 offset:34816
	ds_read_b128 v[188:191], v147 offset:35840
	ds_read_b128 v[192:195], v147 offset:36864
	ds_read_b128 v[196:199], v147 offset:37888
	ds_read_b128 v[200:203], v147 offset:38912
	ds_read_b128 v[204:207], v147 offset:39936
	global_load_lds_dwordx4 v[216:217], off
	v_lshl_add_u64 v[216:217], s[38:39], 0, v[132:133]
	s_mov_b32 m0, s47
	s_nop 0
	global_load_lds_dwordx4 v[216:217], off
	s_waitcnt vmcnt(8)
	s_waitcnt lgkmcnt(0)
	s_barrier
	s_waitcnt lgkmcnt(0)
	v_mfma_f32_16x16x32_bf16 v[122:125], v[140:143], v[176:179], v[122:125]
	v_mfma_f32_16x16x32_bf16 v[114:117], v[152:155], v[176:179], v[114:117]
	v_mfma_f32_16x16x32_bf16 v[106:109], v[140:143], v[184:187], v[106:109]
	v_mfma_f32_16x16x32_bf16 v[98:101], v[152:155], v[184:187], v[98:101]
	v_mfma_f32_16x16x32_bf16 v[90:93], v[140:143], v[192:195], v[90:93]
	v_mfma_f32_16x16x32_bf16 v[82:85], v[152:155], v[192:195], v[82:85]
	v_mfma_f32_16x16x32_bf16 v[74:77], v[140:143], v[200:203], v[74:77]
	v_mfma_f32_16x16x32_bf16 v[66:69], v[152:155], v[200:203], v[66:69]
	v_mfma_f32_16x16x32_bf16 v[122:125], v[148:151], v[180:183], v[122:125]
	v_mfma_f32_16x16x32_bf16 v[114:117], v[156:159], v[180:183], v[114:117]
	v_mfma_f32_16x16x32_bf16 v[106:109], v[148:151], v[188:191], v[106:109]
	v_mfma_f32_16x16x32_bf16 v[98:101], v[156:159], v[188:191], v[98:101]
	v_mfma_f32_16x16x32_bf16 v[90:93], v[148:151], v[196:199], v[90:93]
	v_mfma_f32_16x16x32_bf16 v[82:85], v[156:159], v[196:199], v[82:85]
	v_mfma_f32_16x16x32_bf16 v[74:77], v[148:151], v[204:207], v[74:77]
	v_mfma_f32_16x16x32_bf16 v[66:69], v[156:159], v[204:207], v[66:69]
	v_mfma_f32_16x16x32_bf16 v[126:129], v[160:163], v[176:179], v[126:129]
	v_mfma_f32_16x16x32_bf16 v[118:121], v[168:171], v[176:179], v[118:121]
	v_mfma_f32_16x16x32_bf16 v[110:113], v[160:163], v[184:187], v[110:113]
	v_mfma_f32_16x16x32_bf16 v[102:105], v[168:171], v[184:187], v[102:105]
	v_mfma_f32_16x16x32_bf16 v[94:97], v[160:163], v[192:195], v[94:97]
	v_mfma_f32_16x16x32_bf16 v[86:89], v[168:171], v[192:195], v[86:89]
	v_mfma_f32_16x16x32_bf16 v[78:81], v[160:163], v[200:203], v[78:81]
	v_mfma_f32_16x16x32_bf16 v[70:73], v[168:171], v[200:203], v[70:73]
	v_mfma_f32_16x16x32_bf16 v[126:129], v[164:167], v[180:183], v[126:129]
	v_mfma_f32_16x16x32_bf16 v[118:121], v[172:175], v[180:183], v[118:121]
	v_mfma_f32_16x16x32_bf16 v[110:113], v[164:167], v[188:191], v[110:113]
	v_mfma_f32_16x16x32_bf16 v[102:105], v[172:175], v[188:191], v[102:105]
	v_mfma_f32_16x16x32_bf16 v[94:97], v[164:167], v[196:199], v[94:97]
	v_mfma_f32_16x16x32_bf16 v[86:89], v[172:175], v[196:199], v[86:89]
	v_mfma_f32_16x16x32_bf16 v[78:81], v[164:167], v[204:207], v[78:81]
	v_mfma_f32_16x16x32_bf16 v[70:73], v[172:175], v[204:207], v[70:73]
	s_barrier
	s_add_i32 s38, s57, s43
	v_lshl_add_u64 v[208:209], v[208:209], 0, s[98:99]
	s_mov_b32 m0, s38
	ds_read_b128 v[176:179], v147 offset:49152
	ds_read_b128 v[180:183], v147 offset:50176
	ds_read_b128 v[184:187], v147 offset:51200
	ds_read_b128 v[188:191], v147 offset:52224
	ds_read_b128 v[192:195], v147 offset:53248
	ds_read_b128 v[196:199], v147 offset:54272
	ds_read_b128 v[200:203], v147 offset:55296
	ds_read_b128 v[204:207], v147 offset:56320
	global_load_lds_dwordx4 v[208:209], off
	s_add_i32 m0, s38, 0x2000
	s_add_u32 s30, s30, 0x40080
	v_lshl_add_u64 v[208:209], v[210:211], 0, s[98:99]
	s_addc_u32 s31, s31, 0
	s_add_i32 s38, s58, s43
	global_load_lds_dwordx4 v[208:209], off
	v_lshl_add_u64 v[208:209], s[30:31], 0, v[0:1]
	s_mov_b32 m0, s38
	s_nop 0
	global_load_lds_dwordx4 v[208:209], off
	v_lshl_add_u64 v[208:209], s[30:31], 0, v[134:135]
	s_add_i32 m0, s38, 0x2000
	s_nop 0
	global_load_lds_dwordx4 v[208:209], off
	v_lshl_add_u64 v[208:209], v[212:213], 0, s[98:99]
	s_mov_b32 m0, s49
	s_nop 0
	global_load_lds_dwordx4 v[208:209], off
	v_lshl_add_u64 v[208:209], v[214:215], 0, s[98:99]
	s_mov_b32 m0, s51
	s_nop 0
	global_load_lds_dwordx4 v[208:209], off
	s_waitcnt vmcnt(8)
	s_waitcnt lgkmcnt(0)
	s_barrier
	s_waitcnt lgkmcnt(0)
	v_mfma_f32_16x16x32_bf16 v[58:61], v[140:143], v[176:179], v[58:61]
	v_mfma_f32_16x16x32_bf16 v[50:53], v[152:155], v[176:179], v[50:53]
	v_mfma_f32_16x16x32_bf16 v[42:45], v[140:143], v[184:187], v[42:45]
	v_mfma_f32_16x16x32_bf16 v[34:37], v[152:155], v[184:187], v[34:37]
	v_mfma_f32_16x16x32_bf16 v[26:29], v[140:143], v[192:195], v[26:29]
	v_mfma_f32_16x16x32_bf16 v[18:21], v[152:155], v[192:195], v[18:21]
	v_mfma_f32_16x16x32_bf16 v[10:13], v[140:143], v[200:203], v[10:13]
	v_mfma_f32_16x16x32_bf16 v[6:9], v[152:155], v[200:203], v[6:9]
	v_mfma_f32_16x16x32_bf16 v[58:61], v[148:151], v[180:183], v[58:61]
	v_mfma_f32_16x16x32_bf16 v[50:53], v[156:159], v[180:183], v[50:53]
	v_mfma_f32_16x16x32_bf16 v[42:45], v[148:151], v[188:191], v[42:45]
	v_mfma_f32_16x16x32_bf16 v[34:37], v[156:159], v[188:191], v[34:37]
	v_mfma_f32_16x16x32_bf16 v[26:29], v[148:151], v[196:199], v[26:29]
	v_mfma_f32_16x16x32_bf16 v[18:21], v[156:159], v[196:199], v[18:21]
	v_mfma_f32_16x16x32_bf16 v[10:13], v[148:151], v[204:207], v[10:13]
	v_mfma_f32_16x16x32_bf16 v[6:9], v[156:159], v[204:207], v[6:9]
	v_mfma_f32_16x16x32_bf16 v[62:65], v[160:163], v[176:179], v[62:65]
	v_mfma_f32_16x16x32_bf16 v[54:57], v[168:171], v[176:179], v[54:57]
	v_mfma_f32_16x16x32_bf16 v[46:49], v[160:163], v[184:187], v[46:49]
	v_mfma_f32_16x16x32_bf16 v[38:41], v[168:171], v[184:187], v[38:41]
	v_mfma_f32_16x16x32_bf16 v[30:33], v[160:163], v[192:195], v[30:33]
	v_mfma_f32_16x16x32_bf16 v[22:25], v[168:171], v[192:195], v[22:25]
	v_mfma_f32_16x16x32_bf16 v[14:17], v[160:163], v[200:203], v[14:17]
	v_mfma_f32_16x16x32_bf16 v[2:5], v[168:171], v[200:203], v[2:5]
	v_mfma_f32_16x16x32_bf16 v[62:65], v[164:167], v[180:183], v[62:65]
	v_mfma_f32_16x16x32_bf16 v[54:57], v[172:175], v[180:183], v[54:57]
	v_mfma_f32_16x16x32_bf16 v[46:49], v[164:167], v[188:191], v[46:49]
	v_mfma_f32_16x16x32_bf16 v[38:41], v[172:175], v[188:191], v[38:41]
	v_mfma_f32_16x16x32_bf16 v[30:33], v[164:167], v[196:199], v[30:33]
	v_mfma_f32_16x16x32_bf16 v[22:25], v[172:175], v[196:199], v[22:25]
	v_mfma_f32_16x16x32_bf16 v[14:17], v[164:167], v[204:207], v[14:17]
	v_mfma_f32_16x16x32_bf16 v[2:5], v[172:175], v[204:207], v[2:5]
	s_barrier
	s_add_i32 s56, s56, 2
	s_add_u32 s28, s28, 0x100
	s_addc_u32 s29, s29, 0
	s_add_u32 s54, s54, 0x100
	s_addc_u32 s55, s55, 0
	s_cmp_gt_u32 s56, 13
	s_cbranch_scc1 .Lpeel_done_374
.LBB0_374:
	s_add_u32 s30, s28, 0xfffc0080
	s_addc_u32 s31, s29, -1
	s_add_i32 s57, 0, 0x10000
	s_cmp_eq_u32 s56, 12
	s_cselect_b32 s39, s17, s31
	s_cselect_b32 s38, s25, s30
	s_cselect_b32 s31, s15, s55
	s_cselect_b32 s30, s53, s54
	s_add_i32 s60, 0, 0x14000
	v_add_u32_e32 v156, s57, v145
	v_add_u32_e32 v172, s60, v145
	ds_read_b128 v[140:143], v156
	ds_read_b128 v[148:151], v156 offset:1024
	ds_read_b128 v[152:155], v156 offset:2048
	ds_read_b128 v[156:159], v156 offset:3072
	ds_read_b128 v[160:163], v172
	ds_read_b128 v[164:167], v172 offset:1024
	ds_read_b128 v[168:171], v172 offset:2048
	ds_read_b128 v[172:175], v172 offset:3072
	v_lshl_add_u64 v[208:209], s[28:29], 0, v[136:137]
	s_add_i32 m0, s27, 0xc000
	ds_read_b128 v[176:179], v147
	ds_read_b128 v[180:183], v147 offset:1024
	ds_read_b128 v[184:187], v147 offset:2048
	ds_read_b128 v[188:191], v147 offset:3072
	ds_read_b128 v[192:195], v147 offset:4096
	ds_read_b128 v[196:199], v147 offset:5120
	ds_read_b128 v[200:203], v147 offset:6144
	ds_read_b128 v[204:207], v147 offset:7168
	global_load_lds_dwordx4 v[208:209], off
	v_lshl_add_u64 v[208:209], s[28:29], 0, v[138:139]
	s_add_i32 m0, s27, 0xe000
	s_nop 0
	global_load_lds_dwordx4 v[208:209], off
	s_waitcnt vmcnt(8)
	s_waitcnt lgkmcnt(0)
	s_barrier
	s_waitcnt lgkmcnt(0)
	v_mfma_f32_16x16x32_bf16 v[122:125], v[140:143], v[176:179], v[122:125]
	v_mfma_f32_16x16x32_bf16 v[114:117], v[152:155], v[176:179], v[114:117]
	v_mfma_f32_16x16x32_bf16 v[106:109], v[140:143], v[184:187], v[106:109]
	v_mfma_f32_16x16x32_bf16 v[98:101], v[152:155], v[184:187], v[98:101]
	v_mfma_f32_16x16x32_bf16 v[90:93], v[140:143], v[192:195], v[90:93]
	v_mfma_f32_16x16x32_bf16 v[82:85], v[152:155], v[192:195], v[82:85]
	v_mfma_f32_16x16x32_bf16 v[74:77], v[140:143], v[200:203], v[74:77]
	v_mfma_f32_16x16x32_bf16 v[66:69], v[152:155], v[200:203], v[66:69]
	v_mfma_f32_16x16x32_bf16 v[122:125], v[148:151], v[180:183], v[122:125]
	v_mfma_f32_16x16x32_bf16 v[114:117], v[156:159], v[180:183], v[114:117]
	v_mfma_f32_16x16x32_bf16 v[106:109], v[148:151], v[188:191], v[106:109]
	v_mfma_f32_16x16x32_bf16 v[98:101], v[156:159], v[188:191], v[98:101]
	v_mfma_f32_16x16x32_bf16 v[90:93], v[148:151], v[196:199], v[90:93]
	v_mfma_f32_16x16x32_bf16 v[82:85], v[156:159], v[196:199], v[82:85]
	v_mfma_f32_16x16x32_bf16 v[74:77], v[148:151], v[204:207], v[74:77]
	v_mfma_f32_16x16x32_bf16 v[66:69], v[156:159], v[204:207], v[66:69]
	v_mfma_f32_16x16x32_bf16 v[126:129], v[160:163], v[176:179], v[126:129]
	v_mfma_f32_16x16x32_bf16 v[118:121], v[168:171], v[176:179], v[118:121]
	v_mfma_f32_16x16x32_bf16 v[110:113], v[160:163], v[184:187], v[110:113]
	v_mfma_f32_16x16x32_bf16 v[102:105], v[168:171], v[184:187], v[102:105]
	v_mfma_f32_16x16x32_bf16 v[94:97], v[160:163], v[192:195], v[94:97]
	v_mfma_f32_16x16x32_bf16 v[86:89], v[168:171], v[192:195], v[86:89]
	v_mfma_f32_16x16x32_bf16 v[78:81], v[160:163], v[200:203], v[78:81]
	v_mfma_f32_16x16x32_bf16 v[70:73], v[168:171], v[200:203], v[70:73]
	v_mfma_f32_16x16x32_bf16 v[126:129], v[164:167], v[180:183], v[126:129]
	v_mfma_f32_16x16x32_bf16 v[118:121], v[172:175], v[180:183], v[118:121]
	v_mfma_f32_16x16x32_bf16 v[110:113], v[164:167], v[188:191], v[110:113]
	v_mfma_f32_16x16x32_bf16 v[102:105], v[172:175], v[188:191], v[102:105]
	v_mfma_f32_16x16x32_bf16 v[94:97], v[164:167], v[196:199], v[94:97]
	v_mfma_f32_16x16x32_bf16 v[86:89], v[172:175], v[196:199], v[86:89]
	v_mfma_f32_16x16x32_bf16 v[78:81], v[164:167], v[204:207], v[78:81]
	v_mfma_f32_16x16x32_bf16 v[70:73], v[172:175], v[204:207], v[70:73]
	s_barrier
	s_add_i32 s57, s57, s43
	v_lshl_add_u64 v[208:209], s[30:31], 0, v[0:1]
	s_mov_b32 m0, s57
	ds_read_b128 v[176:179], v147 offset:16384
	ds_read_b128 v[180:183], v147 offset:17408
	ds_read_b128 v[184:187], v147 offset:18432
	ds_read_b128 v[188:191], v147 offset:19456
	ds_read_b128 v[192:195], v147 offset:20480
	ds_read_b128 v[196:199], v147 offset:21504
	ds_read_b128 v[200:203], v147 offset:22528
	ds_read_b128 v[204:207], v147 offset:23552
	global_load_lds_dwordx4 v[208:209], off
	s_add_i32 m0, s57, 0x2000
	s_add_u32 s58, s30, 0x40000
	v_lshl_add_u64 v[210:211], s[30:31], 0, v[134:135]
	s_addc_u32 s59, s31, 0
	s_add_i32 s57, s60, s43
	global_load_lds_dwordx4 v[210:211], off
	v_lshl_add_u64 v[212:213], s[58:59], 0, v[0:1]
	s_mov_b32 m0, s57
	v_lshl_add_u64 v[214:215], s[38:39], 0, v[132:133]
	global_load_lds_dwordx4 v[212:213], off
	v_lshl_add_u64 v[212:213], s[58:59], 0, v[134:135]
	s_add_i32 m0, s57, 0x2000
	s_nop 0
	global_load_lds_dwordx4 v[212:213], off
	v_lshl_add_u64 v[212:213], s[38:39], 0, v[130:131]
	s_mov_b32 m0, s27
	s_nop 0
	global_load_lds_dwordx4 v[212:213], off
	s_mov_b32 m0, s44
	s_nop 0
	global_load_lds_dwordx4 v[214:215], off
	s_waitcnt vmcnt(8)
	s_waitcnt lgkmcnt(0)
	s_barrier
	s_waitcnt lgkmcnt(0)
	v_mfma_f32_16x16x32_bf16 v[58:61], v[140:143], v[176:179], v[58:61]
	v_mfma_f32_16x16x32_bf16 v[50:53], v[152:155], v[176:179], v[50:53]
	v_mfma_f32_16x16x32_bf16 v[42:45], v[140:143], v[184:187], v[42:45]
	v_mfma_f32_16x16x32_bf16 v[34:37], v[152:155], v[184:187], v[34:37]
	v_mfma_f32_16x16x32_bf16 v[26:29], v[140:143], v[192:195], v[26:29]
	v_mfma_f32_16x16x32_bf16 v[18:21], v[152:155], v[192:195], v[18:21]
	v_mfma_f32_16x16x32_bf16 v[10:13], v[140:143], v[200:203], v[10:13]
	v_mfma_f32_16x16x32_bf16 v[6:9], v[152:155], v[200:203], v[6:9]
	v_mfma_f32_16x16x32_bf16 v[58:61], v[148:151], v[180:183], v[58:61]
	v_mfma_f32_16x16x32_bf16 v[50:53], v[156:159], v[180:183], v[50:53]
	v_mfma_f32_16x16x32_bf16 v[42:45], v[148:151], v[188:191], v[42:45]
	v_mfma_f32_16x16x32_bf16 v[34:37], v[156:159], v[188:191], v[34:37]
	v_mfma_f32_16x16x32_bf16 v[26:29], v[148:151], v[196:199], v[26:29]
	v_mfma_f32_16x16x32_bf16 v[18:21], v[156:159], v[196:199], v[18:21]
	v_mfma_f32_16x16x32_bf16 v[10:13], v[148:151], v[204:207], v[10:13]
	v_mfma_f32_16x16x32_bf16 v[6:9], v[156:159], v[204:207], v[6:9]
	v_mfma_f32_16x16x32_bf16 v[62:65], v[160:163], v[176:179], v[62:65]
	v_mfma_f32_16x16x32_bf16 v[54:57], v[168:171], v[176:179], v[54:57]
	v_mfma_f32_16x16x32_bf16 v[46:49], v[160:163], v[184:187], v[46:49]
	v_mfma_f32_16x16x32_bf16 v[38:41], v[168:171], v[184:187], v[38:41]
	v_mfma_f32_16x16x32_bf16 v[30:33], v[160:163], v[192:195], v[30:33]
	v_mfma_f32_16x16x32_bf16 v[22:25], v[168:171], v[192:195], v[22:25]
	v_mfma_f32_16x16x32_bf16 v[14:17], v[160:163], v[200:203], v[14:17]
	v_mfma_f32_16x16x32_bf16 v[2:5], v[168:171], v[200:203], v[2:5]
	v_mfma_f32_16x16x32_bf16 v[62:65], v[164:167], v[180:183], v[62:65]
	v_mfma_f32_16x16x32_bf16 v[54:57], v[172:175], v[180:183], v[54:57]
	v_mfma_f32_16x16x32_bf16 v[46:49], v[164:167], v[188:191], v[46:49]
	v_mfma_f32_16x16x32_bf16 v[38:41], v[172:175], v[188:191], v[38:41]
	v_mfma_f32_16x16x32_bf16 v[30:33], v[164:167], v[196:199], v[30:33]
	v_mfma_f32_16x16x32_bf16 v[22:25], v[172:175], v[196:199], v[22:25]
	v_mfma_f32_16x16x32_bf16 v[14:17], v[164:167], v[204:207], v[14:17]
	v_mfma_f32_16x16x32_bf16 v[2:5], v[172:175], v[204:207], v[2:5]
	s_barrier
	s_add_i32 s57, 0, 0x18000
	s_add_i32 s58, 0, 0x1c000
	v_add_u32_e32 v156, s57, v145
	v_add_u32_e32 v172, s58, v145
	ds_read_b128 v[140:143], v156
	ds_read_b128 v[148:151], v156 offset:1024
	ds_read_b128 v[152:155], v156 offset:2048
	ds_read_b128 v[156:159], v156 offset:3072
	ds_read_b128 v[160:163], v172
	ds_read_b128 v[164:167], v172 offset:1024
	ds_read_b128 v[168:171], v172 offset:2048
	ds_read_b128 v[172:175], v172 offset:3072
	s_add_u32 s38, s38, 0x40000
	s_addc_u32 s39, s39, 0
	s_mov_b32 m0, s45
	v_lshl_add_u64 v[216:217], s[38:39], 0, v[130:131]
	ds_read_b128 v[176:179], v147 offset:32768
	ds_read_b128 v[180:183], v147 offset:33792
	ds_read_b128 v[184:187], v147 offset:34816
	ds_read_b128 v[188:191], v147 offset:35840
	ds_read_b128 v[192:195], v147 offset:36864
	ds_read_b128 v[196:199], v147 offset:37888
	ds_read_b128 v[200:203], v147 offset:38912
	ds_read_b128 v[204:207], v147 offset:39936
	global_load_lds_dwordx4 v[216:217], off
	v_lshl_add_u64 v[216:217], s[38:39], 0, v[132:133]
	s_mov_b32 m0, s47
	s_nop 0
	global_load_lds_dwordx4 v[216:217], off
	s_waitcnt vmcnt(8)
	s_waitcnt lgkmcnt(0)
	s_barrier
	s_waitcnt lgkmcnt(0)
	v_mfma_f32_16x16x32_bf16 v[122:125], v[140:143], v[176:179], v[122:125]
	v_mfma_f32_16x16x32_bf16 v[114:117], v[152:155], v[176:179], v[114:117]
	v_mfma_f32_16x16x32_bf16 v[106:109], v[140:143], v[184:187], v[106:109]
	v_mfma_f32_16x16x32_bf16 v[98:101], v[152:155], v[184:187], v[98:101]
	v_mfma_f32_16x16x32_bf16 v[90:93], v[140:143], v[192:195], v[90:93]
	v_mfma_f32_16x16x32_bf16 v[82:85], v[152:155], v[192:195], v[82:85]
	v_mfma_f32_16x16x32_bf16 v[74:77], v[140:143], v[200:203], v[74:77]
	v_mfma_f32_16x16x32_bf16 v[66:69], v[152:155], v[200:203], v[66:69]
	v_mfma_f32_16x16x32_bf16 v[122:125], v[148:151], v[180:183], v[122:125]
	v_mfma_f32_16x16x32_bf16 v[114:117], v[156:159], v[180:183], v[114:117]
	v_mfma_f32_16x16x32_bf16 v[106:109], v[148:151], v[188:191], v[106:109]
	v_mfma_f32_16x16x32_bf16 v[98:101], v[156:159], v[188:191], v[98:101]
	v_mfma_f32_16x16x32_bf16 v[90:93], v[148:151], v[196:199], v[90:93]
	v_mfma_f32_16x16x32_bf16 v[82:85], v[156:159], v[196:199], v[82:85]
	v_mfma_f32_16x16x32_bf16 v[74:77], v[148:151], v[204:207], v[74:77]
	v_mfma_f32_16x16x32_bf16 v[66:69], v[156:159], v[204:207], v[66:69]
	v_mfma_f32_16x16x32_bf16 v[126:129], v[160:163], v[176:179], v[126:129]
	v_mfma_f32_16x16x32_bf16 v[118:121], v[168:171], v[176:179], v[118:121]
	v_mfma_f32_16x16x32_bf16 v[110:113], v[160:163], v[184:187], v[110:113]
	v_mfma_f32_16x16x32_bf16 v[102:105], v[168:171], v[184:187], v[102:105]
	v_mfma_f32_16x16x32_bf16 v[94:97], v[160:163], v[192:195], v[94:97]
	v_mfma_f32_16x16x32_bf16 v[86:89], v[168:171], v[192:195], v[86:89]
	v_mfma_f32_16x16x32_bf16 v[78:81], v[160:163], v[200:203], v[78:81]
	v_mfma_f32_16x16x32_bf16 v[70:73], v[168:171], v[200:203], v[70:73]
	v_mfma_f32_16x16x32_bf16 v[126:129], v[164:167], v[180:183], v[126:129]
	v_mfma_f32_16x16x32_bf16 v[118:121], v[172:175], v[180:183], v[118:121]
	v_mfma_f32_16x16x32_bf16 v[110:113], v[164:167], v[188:191], v[110:113]
	v_mfma_f32_16x16x32_bf16 v[102:105], v[172:175], v[188:191], v[102:105]
	v_mfma_f32_16x16x32_bf16 v[94:97], v[164:167], v[196:199], v[94:97]
	v_mfma_f32_16x16x32_bf16 v[86:89], v[172:175], v[196:199], v[86:89]
	v_mfma_f32_16x16x32_bf16 v[78:81], v[164:167], v[204:207], v[78:81]
	v_mfma_f32_16x16x32_bf16 v[70:73], v[172:175], v[204:207], v[70:73]
	s_barrier
	s_add_i32 s38, s57, s43
	v_lshl_add_u64 v[208:209], v[208:209], 0, s[98:99]
	s_mov_b32 m0, s38
	ds_read_b128 v[176:179], v147 offset:49152
	ds_read_b128 v[180:183], v147 offset:50176
	ds_read_b128 v[184:187], v147 offset:51200
	ds_read_b128 v[188:191], v147 offset:52224
	ds_read_b128 v[192:195], v147 offset:53248
	ds_read_b128 v[196:199], v147 offset:54272
	ds_read_b128 v[200:203], v147 offset:55296
	ds_read_b128 v[204:207], v147 offset:56320
	global_load_lds_dwordx4 v[208:209], off
	s_add_i32 m0, s38, 0x2000
	s_add_u32 s30, s30, 0x40080
	v_lshl_add_u64 v[208:209], v[210:211], 0, s[98:99]
	s_addc_u32 s31, s31, 0
	s_add_i32 s38, s58, s43
	global_load_lds_dwordx4 v[208:209], off
	v_lshl_add_u64 v[208:209], s[30:31], 0, v[0:1]
	s_mov_b32 m0, s38
	s_nop 0
	global_load_lds_dwordx4 v[208:209], off
	v_lshl_add_u64 v[208:209], s[30:31], 0, v[134:135]
	s_add_i32 m0, s38, 0x2000
	s_nop 0
	global_load_lds_dwordx4 v[208:209], off
	v_lshl_add_u64 v[208:209], v[212:213], 0, s[98:99]
	s_mov_b32 m0, s49
	s_nop 0
	global_load_lds_dwordx4 v[208:209], off
	v_lshl_add_u64 v[208:209], v[214:215], 0, s[98:99]
	s_mov_b32 m0, s51
	s_nop 0
	global_load_lds_dwordx4 v[208:209], off
	s_waitcnt vmcnt(8)
	s_waitcnt lgkmcnt(0)
	s_barrier
	s_waitcnt lgkmcnt(0)
	v_mfma_f32_16x16x32_bf16 v[58:61], v[140:143], v[176:179], v[58:61]
	v_mfma_f32_16x16x32_bf16 v[50:53], v[152:155], v[176:179], v[50:53]
	v_mfma_f32_16x16x32_bf16 v[42:45], v[140:143], v[184:187], v[42:45]
	v_mfma_f32_16x16x32_bf16 v[34:37], v[152:155], v[184:187], v[34:37]
	v_mfma_f32_16x16x32_bf16 v[26:29], v[140:143], v[192:195], v[26:29]
	v_mfma_f32_16x16x32_bf16 v[18:21], v[152:155], v[192:195], v[18:21]
	v_mfma_f32_16x16x32_bf16 v[10:13], v[140:143], v[200:203], v[10:13]
	v_mfma_f32_16x16x32_bf16 v[6:9], v[152:155], v[200:203], v[6:9]
	v_mfma_f32_16x16x32_bf16 v[58:61], v[148:151], v[180:183], v[58:61]
	v_mfma_f32_16x16x32_bf16 v[50:53], v[156:159], v[180:183], v[50:53]
	v_mfma_f32_16x16x32_bf16 v[42:45], v[148:151], v[188:191], v[42:45]
	v_mfma_f32_16x16x32_bf16 v[34:37], v[156:159], v[188:191], v[34:37]
	v_mfma_f32_16x16x32_bf16 v[26:29], v[148:151], v[196:199], v[26:29]
	v_mfma_f32_16x16x32_bf16 v[18:21], v[156:159], v[196:199], v[18:21]
	v_mfma_f32_16x16x32_bf16 v[10:13], v[148:151], v[204:207], v[10:13]
	v_mfma_f32_16x16x32_bf16 v[6:9], v[156:159], v[204:207], v[6:9]
	v_mfma_f32_16x16x32_bf16 v[62:65], v[160:163], v[176:179], v[62:65]
	v_mfma_f32_16x16x32_bf16 v[54:57], v[168:171], v[176:179], v[54:57]
	v_mfma_f32_16x16x32_bf16 v[46:49], v[160:163], v[184:187], v[46:49]
	v_mfma_f32_16x16x32_bf16 v[38:41], v[168:171], v[184:187], v[38:41]
	v_mfma_f32_16x16x32_bf16 v[30:33], v[160:163], v[192:195], v[30:33]
	v_mfma_f32_16x16x32_bf16 v[22:25], v[168:171], v[192:195], v[22:25]
	v_mfma_f32_16x16x32_bf16 v[14:17], v[160:163], v[200:203], v[14:17]
	v_mfma_f32_16x16x32_bf16 v[2:5], v[168:171], v[200:203], v[2:5]
	v_mfma_f32_16x16x32_bf16 v[62:65], v[164:167], v[180:183], v[62:65]
	v_mfma_f32_16x16x32_bf16 v[54:57], v[172:175], v[180:183], v[54:57]
	v_mfma_f32_16x16x32_bf16 v[46:49], v[164:167], v[188:191], v[46:49]
	v_mfma_f32_16x16x32_bf16 v[38:41], v[172:175], v[188:191], v[38:41]
	v_mfma_f32_16x16x32_bf16 v[30:33], v[164:167], v[196:199], v[30:33]
	v_mfma_f32_16x16x32_bf16 v[22:25], v[172:175], v[196:199], v[22:25]
	v_mfma_f32_16x16x32_bf16 v[14:17], v[164:167], v[204:207], v[14:17]
	v_mfma_f32_16x16x32_bf16 v[2:5], v[172:175], v[204:207], v[2:5]
	s_barrier
	s_add_i32 s56, s56, 2
	s_add_u32 s28, s28, 0x100
	s_addc_u32 s29, s29, 0
	s_add_u32 s54, s54, 0x100
	s_addc_u32 s55, s55, 0
	s_cmp_gt_u32 s56, 13
	s_cbranch_scc0 .LBB0_374
